# down and up k-loops: barrier three MFMAs later in each step (12 instead of 15 MFMAs of the last group after it)
# speedup vs baseline: 1.1132x; 1.0009x over previous
.LBB0_2305:
	s_waitcnt lgkmcnt(0)
	s_mov_b32 s99, 0x10000
	s_mov_b32 s100, 0x80
	s_mov_b32 s101, 0
	s_add_i32 m0, s93, 0x10000
	s_nop 0
	global_load_lds_dwordx4 v[128:129], off
	v_lshl_add_u64 v[128:129], v[128:129], 0, s[100:101]
	s_add_i32 m0, s93, 0x18000
	s_nop 0
	global_load_lds_dwordx4 v[140:141], off
	v_lshl_add_u64 v[140:141], v[140:141], 0, s[100:101]
	s_add_i32 m0, s94, 0x10000
	s_nop 0
	global_load_lds_dwordx4 v[130:131], off
	v_lshl_add_u64 v[130:131], v[130:131], 0, s[100:101]
	s_add_i32 m0, s94, 0x18000
	s_nop 0
	global_load_lds_dwordx4 v[142:143], off
	v_lshl_add_u64 v[142:143], v[142:143], 0, s[100:101]
	s_add_i32 m0, s95, 0x10000
	s_nop 0
	global_load_lds_dwordx4 v[136:137], off
	v_lshl_add_u64 v[136:137], v[136:137], 0, s[100:101]
	s_add_i32 m0, s95, 0x18000
	s_nop 0
	global_load_lds_dwordx4 v[144:145], off
	v_lshl_add_u64 v[144:145], v[144:145], 0, s[100:101]
	s_add_i32 m0, s96, 0x10000
	s_nop 0
	global_load_lds_dwordx4 v[138:139], off
	v_lshl_add_u64 v[138:139], v[138:139], 0, s[100:101]
	s_add_i32 m0, s96, 0x18000
	s_nop 0
	global_load_lds_dwordx4 v[146:147], off
	v_lshl_add_u64 v[146:147], v[146:147], 0, s[100:101]
	v_add_u32_e32 v164, v151, v150
	v_add_u32_e32 v134, v151, v148
	ds_read_b128 v[152:155], v164 offset:32768
	ds_read_b128 v[156:159], v164 offset:34816
	ds_read_b128 v[160:163], v164 offset:36864
	ds_read_b128 v[164:167], v164 offset:38912
	ds_read_b128 v[168:171], v134 offset:0
	ds_read_b128 v[172:175], v134 offset:2048
	ds_read_b128 v[176:179], v134 offset:4096
	ds_read_b128 v[180:183], v134 offset:6144
	ds_read_b128 v[198:201], v134 offset:8192
	ds_read_b128 v[202:205], v134 offset:10240
	ds_read_b128 v[206:209], v134 offset:12288
	ds_read_b128 v[210:213], v134 offset:14336
	s_waitcnt lgkmcnt(4)
	v_mfma_f32_16x16x32_bf16 v[124:127], v[168:171], v[152:155], 0
	v_mfma_f32_16x16x32_bf16 v[120:123], v[168:171], v[156:159], 0
	v_mfma_f32_16x16x32_bf16 v[116:119], v[168:171], v[160:163], 0
	v_mfma_f32_16x16x32_bf16 v[112:115], v[168:171], v[164:167], 0
	v_mfma_f32_16x16x32_bf16 v[108:111], v[172:175], v[152:155], 0
	v_mfma_f32_16x16x32_bf16 v[104:107], v[172:175], v[156:159], 0
	v_mfma_f32_16x16x32_bf16 v[100:103], v[172:175], v[160:163], 0
	v_mfma_f32_16x16x32_bf16 v[96:99], v[172:175], v[164:167], 0
	v_mfma_f32_16x16x32_bf16 v[92:95], v[176:179], v[152:155], 0
	v_mfma_f32_16x16x32_bf16 v[84:87], v[176:179], v[156:159], 0
	v_mfma_f32_16x16x32_bf16 v[80:83], v[176:179], v[160:163], 0
	v_mfma_f32_16x16x32_bf16 v[76:79], v[176:179], v[164:167], 0
	v_mfma_f32_16x16x32_bf16 v[72:75], v[180:183], v[152:155], 0
	v_mfma_f32_16x16x32_bf16 v[68:71], v[180:183], v[156:159], 0
	v_mfma_f32_16x16x32_bf16 v[64:67], v[180:183], v[160:163], 0
	v_mfma_f32_16x16x32_bf16 v[60:63], v[180:183], v[164:167], 0
	v_add_u32_e32 v180, v149, v150
	v_add_u32_e32 v134, v149, v148
	ds_read_b128 v[168:171], v180 offset:32768
	ds_read_b128 v[172:175], v180 offset:34816
	ds_read_b128 v[176:179], v180 offset:36864
	ds_read_b128 v[180:183], v180 offset:38912
	ds_read_b128 v[214:217], v134 offset:0
	ds_read_b128 v[218:221], v134 offset:2048
	ds_read_b128 v[222:225], v134 offset:4096
	ds_read_b128 v[226:229], v134 offset:6144
	s_waitcnt lgkmcnt(8)
	v_mfma_f32_16x16x32_bf16 v[56:59], v[198:201], v[152:155], 0
	v_mfma_f32_16x16x32_bf16 v[52:55], v[198:201], v[156:159], 0
	v_mfma_f32_16x16x32_bf16 v[48:51], v[198:201], v[160:163], 0
	v_mfma_f32_16x16x32_bf16 v[44:47], v[198:201], v[164:167], 0
	v_mfma_f32_16x16x32_bf16 v[40:43], v[202:205], v[152:155], 0
	v_mfma_f32_16x16x32_bf16 v[36:39], v[202:205], v[156:159], 0
	v_mfma_f32_16x16x32_bf16 v[32:35], v[202:205], v[160:163], 0
	v_mfma_f32_16x16x32_bf16 v[28:31], v[202:205], v[164:167], 0
	v_mfma_f32_16x16x32_bf16 v[24:27], v[206:209], v[152:155], 0
	v_mfma_f32_16x16x32_bf16 v[20:23], v[206:209], v[156:159], 0
	v_mfma_f32_16x16x32_bf16 v[16:19], v[206:209], v[160:163], 0
	v_mfma_f32_16x16x32_bf16 v[12:15], v[206:209], v[164:167], 0
	v_mfma_f32_16x16x32_bf16 v[8:11], v[210:213], v[152:155], 0
	v_mfma_f32_16x16x32_bf16 v[4:7], v[210:213], v[156:159], 0
	v_mfma_f32_16x16x32_bf16 v[0:3], v[210:213], v[160:163], 0
	v_mfma_f32_16x16x32_bf16 v[88:91], v[210:213], v[164:167], 0
	ds_read_b128 v[152:155], v134 offset:8192
	ds_read_b128 v[156:159], v134 offset:10240
	ds_read_b128 v[160:163], v134 offset:12288
	ds_read_b128 v[164:167], v134 offset:14336
	s_waitcnt lgkmcnt(4)
	v_mfma_f32_16x16x32_bf16 v[124:127], v[214:217], v[168:171], v[124:127]
	v_mfma_f32_16x16x32_bf16 v[120:123], v[214:217], v[172:175], v[120:123]
	v_mfma_f32_16x16x32_bf16 v[116:119], v[214:217], v[176:179], v[116:119]
	v_mfma_f32_16x16x32_bf16 v[112:115], v[214:217], v[180:183], v[112:115]
	v_mfma_f32_16x16x32_bf16 v[108:111], v[218:221], v[168:171], v[108:111]
	v_mfma_f32_16x16x32_bf16 v[104:107], v[218:221], v[172:175], v[104:107]
	v_mfma_f32_16x16x32_bf16 v[100:103], v[218:221], v[176:179], v[100:103]
	v_mfma_f32_16x16x32_bf16 v[96:99], v[218:221], v[180:183], v[96:99]
	v_mfma_f32_16x16x32_bf16 v[92:95], v[222:225], v[168:171], v[92:95]
	v_mfma_f32_16x16x32_bf16 v[84:87], v[222:225], v[172:175], v[84:87]
	v_mfma_f32_16x16x32_bf16 v[80:83], v[222:225], v[176:179], v[80:83]
	v_mfma_f32_16x16x32_bf16 v[76:79], v[222:225], v[180:183], v[76:79]
	v_mfma_f32_16x16x32_bf16 v[72:75], v[226:229], v[168:171], v[72:75]
	v_mfma_f32_16x16x32_bf16 v[68:71], v[226:229], v[172:175], v[68:71]
	v_mfma_f32_16x16x32_bf16 v[64:67], v[226:229], v[176:179], v[64:67]
	v_mfma_f32_16x16x32_bf16 v[60:63], v[226:229], v[180:183], v[60:63]
	s_waitcnt lgkmcnt(0)
	v_mfma_f32_16x16x32_bf16 v[56:59], v[152:155], v[168:171], v[56:59]
	v_mfma_f32_16x16x32_bf16 v[52:55], v[152:155], v[172:175], v[52:55]
	v_mfma_f32_16x16x32_bf16 v[48:51], v[152:155], v[176:179], v[48:51]
	v_mfma_f32_16x16x32_bf16 v[44:47], v[152:155], v[180:183], v[44:47]
	s_waitcnt vmcnt(0)
	s_barrier
	v_add3_u32 v210, v151, v150, s99
	v_add3_u32 v134, v151, v148, s99
	v_mfma_f32_16x16x32_bf16 v[40:43], v[156:159], v[168:171], v[40:43]
	ds_read_b128 v[198:201], v210 offset:32768
	ds_read_b128 v[202:205], v210 offset:34816
	v_mfma_f32_16x16x32_bf16 v[36:39], v[156:159], v[172:175], v[36:39]
	ds_read_b128 v[206:209], v210 offset:36864
	ds_read_b128 v[210:213], v210 offset:38912
	v_mfma_f32_16x16x32_bf16 v[32:35], v[156:159], v[176:179], v[32:35]
	ds_read_b128 v[214:217], v134 offset:0
	ds_read_b128 v[218:221], v134 offset:2048
	v_mfma_f32_16x16x32_bf16 v[28:31], v[156:159], v[180:183], v[28:31]
	ds_read_b128 v[222:225], v134 offset:4096
	ds_read_b128 v[226:229], v134 offset:6144
	s_mov_b32 m0, s93
	v_mfma_f32_16x16x32_bf16 v[24:27], v[160:163], v[168:171], v[24:27]
	global_load_lds_dwordx4 v[128:129], off
	v_lshl_add_u64 v[128:129], v[128:129], 0, s[100:101]
	s_add_i32 m0, s93, 0x8000
	v_mfma_f32_16x16x32_bf16 v[20:23], v[160:163], v[172:175], v[20:23]
	global_load_lds_dwordx4 v[140:141], off
	v_lshl_add_u64 v[140:141], v[140:141], 0, s[100:101]
	s_mov_b32 m0, s94
	v_mfma_f32_16x16x32_bf16 v[16:19], v[160:163], v[176:179], v[16:19]
	global_load_lds_dwordx4 v[130:131], off
	v_lshl_add_u64 v[130:131], v[130:131], 0, s[100:101]
	s_add_i32 m0, s94, 0x8000
	v_mfma_f32_16x16x32_bf16 v[12:15], v[160:163], v[180:183], v[12:15]
	global_load_lds_dwordx4 v[142:143], off
	v_lshl_add_u64 v[142:143], v[142:143], 0, s[100:101]
	s_mov_b32 m0, s95
	v_mfma_f32_16x16x32_bf16 v[8:11], v[164:167], v[168:171], v[8:11]
	global_load_lds_dwordx4 v[136:137], off
	v_lshl_add_u64 v[136:137], v[136:137], 0, s[100:101]
	s_add_i32 m0, s95, 0x8000
	v_mfma_f32_16x16x32_bf16 v[4:7], v[164:167], v[172:175], v[4:7]
	global_load_lds_dwordx4 v[144:145], off
	v_lshl_add_u64 v[144:145], v[144:145], 0, s[100:101]
	s_mov_b32 m0, s96
	v_mfma_f32_16x16x32_bf16 v[0:3], v[164:167], v[176:179], v[0:3]
	global_load_lds_dwordx4 v[138:139], off
	v_lshl_add_u64 v[138:139], v[138:139], 0, s[100:101]
	s_add_i32 m0, s96, 0x8000
	v_mfma_f32_16x16x32_bf16 v[88:91], v[164:167], v[180:183], v[88:91]
	global_load_lds_dwordx4 v[146:147], off
	v_lshl_add_u64 v[146:147], v[146:147], 0, s[100:101]
	ds_read_b128 v[152:155], v134 offset:8192
	ds_read_b128 v[156:159], v134 offset:10240
	ds_read_b128 v[160:163], v134 offset:12288
	ds_read_b128 v[164:167], v134 offset:14336
	s_waitcnt lgkmcnt(4)
	v_mfma_f32_16x16x32_bf16 v[124:127], v[214:217], v[198:201], v[124:127]
	v_mfma_f32_16x16x32_bf16 v[120:123], v[214:217], v[202:205], v[120:123]
	v_mfma_f32_16x16x32_bf16 v[116:119], v[214:217], v[206:209], v[116:119]
	v_mfma_f32_16x16x32_bf16 v[112:115], v[214:217], v[210:213], v[112:115]
	v_mfma_f32_16x16x32_bf16 v[108:111], v[218:221], v[198:201], v[108:111]
	v_mfma_f32_16x16x32_bf16 v[104:107], v[218:221], v[202:205], v[104:107]
	v_mfma_f32_16x16x32_bf16 v[100:103], v[218:221], v[206:209], v[100:103]
	v_mfma_f32_16x16x32_bf16 v[96:99], v[218:221], v[210:213], v[96:99]
	v_mfma_f32_16x16x32_bf16 v[92:95], v[222:225], v[198:201], v[92:95]
	v_mfma_f32_16x16x32_bf16 v[84:87], v[222:225], v[202:205], v[84:87]
	v_mfma_f32_16x16x32_bf16 v[80:83], v[222:225], v[206:209], v[80:83]
	v_mfma_f32_16x16x32_bf16 v[76:79], v[222:225], v[210:213], v[76:79]
	v_mfma_f32_16x16x32_bf16 v[72:75], v[226:229], v[198:201], v[72:75]
	v_mfma_f32_16x16x32_bf16 v[68:71], v[226:229], v[202:205], v[68:71]
	v_mfma_f32_16x16x32_bf16 v[64:67], v[226:229], v[206:209], v[64:67]
	v_mfma_f32_16x16x32_bf16 v[60:63], v[226:229], v[210:213], v[60:63]
	v_add3_u32 v226, v149, v150, s99
	v_add3_u32 v134, v149, v148, s99
	ds_read_b128 v[214:217], v226 offset:32768
	ds_read_b128 v[218:221], v226 offset:34816
	ds_read_b128 v[222:225], v226 offset:36864
	ds_read_b128 v[226:229], v226 offset:38912
	ds_read_b128 v[168:171], v134 offset:0
	ds_read_b128 v[172:175], v134 offset:2048
	ds_read_b128 v[176:179], v134 offset:4096
	ds_read_b128 v[180:183], v134 offset:6144
	s_waitcnt lgkmcnt(8)
	v_mfma_f32_16x16x32_bf16 v[56:59], v[152:155], v[198:201], v[56:59]
	v_mfma_f32_16x16x32_bf16 v[52:55], v[152:155], v[202:205], v[52:55]
	v_mfma_f32_16x16x32_bf16 v[48:51], v[152:155], v[206:209], v[48:51]
	v_mfma_f32_16x16x32_bf16 v[44:47], v[152:155], v[210:213], v[44:47]
	v_mfma_f32_16x16x32_bf16 v[40:43], v[156:159], v[198:201], v[40:43]
	v_mfma_f32_16x16x32_bf16 v[36:39], v[156:159], v[202:205], v[36:39]
	v_mfma_f32_16x16x32_bf16 v[32:35], v[156:159], v[206:209], v[32:35]
	v_mfma_f32_16x16x32_bf16 v[28:31], v[156:159], v[210:213], v[28:31]
	v_mfma_f32_16x16x32_bf16 v[24:27], v[160:163], v[198:201], v[24:27]
	v_mfma_f32_16x16x32_bf16 v[20:23], v[160:163], v[202:205], v[20:23]
	v_mfma_f32_16x16x32_bf16 v[16:19], v[160:163], v[206:209], v[16:19]
	v_mfma_f32_16x16x32_bf16 v[12:15], v[160:163], v[210:213], v[12:15]
	v_mfma_f32_16x16x32_bf16 v[8:11], v[164:167], v[198:201], v[8:11]
	v_mfma_f32_16x16x32_bf16 v[4:7], v[164:167], v[202:205], v[4:7]
	v_mfma_f32_16x16x32_bf16 v[0:3], v[164:167], v[206:209], v[0:3]
	v_mfma_f32_16x16x32_bf16 v[88:91], v[164:167], v[210:213], v[88:91]
	ds_read_b128 v[198:201], v134 offset:8192
	ds_read_b128 v[202:205], v134 offset:10240
	ds_read_b128 v[206:209], v134 offset:12288
	ds_read_b128 v[210:213], v134 offset:14336
	s_waitcnt lgkmcnt(4)
	v_mfma_f32_16x16x32_bf16 v[124:127], v[168:171], v[214:217], v[124:127]
	v_mfma_f32_16x16x32_bf16 v[120:123], v[168:171], v[218:221], v[120:123]
	v_mfma_f32_16x16x32_bf16 v[116:119], v[168:171], v[222:225], v[116:119]
	v_mfma_f32_16x16x32_bf16 v[112:115], v[168:171], v[226:229], v[112:115]
	v_mfma_f32_16x16x32_bf16 v[108:111], v[172:175], v[214:217], v[108:111]
	v_mfma_f32_16x16x32_bf16 v[104:107], v[172:175], v[218:221], v[104:107]
	v_mfma_f32_16x16x32_bf16 v[100:103], v[172:175], v[222:225], v[100:103]
	v_mfma_f32_16x16x32_bf16 v[96:99], v[172:175], v[226:229], v[96:99]
	v_mfma_f32_16x16x32_bf16 v[92:95], v[176:179], v[214:217], v[92:95]
	v_mfma_f32_16x16x32_bf16 v[84:87], v[176:179], v[218:221], v[84:87]
	v_mfma_f32_16x16x32_bf16 v[80:83], v[176:179], v[222:225], v[80:83]
	v_mfma_f32_16x16x32_bf16 v[76:79], v[176:179], v[226:229], v[76:79]
	v_mfma_f32_16x16x32_bf16 v[72:75], v[180:183], v[214:217], v[72:75]
	v_mfma_f32_16x16x32_bf16 v[68:71], v[180:183], v[218:221], v[68:71]
	v_mfma_f32_16x16x32_bf16 v[64:67], v[180:183], v[222:225], v[64:67]
	v_mfma_f32_16x16x32_bf16 v[60:63], v[180:183], v[226:229], v[60:63]
	s_waitcnt lgkmcnt(0)
	v_mfma_f32_16x16x32_bf16 v[56:59], v[198:201], v[214:217], v[56:59]
	v_mfma_f32_16x16x32_bf16 v[52:55], v[198:201], v[218:221], v[52:55]
	v_mfma_f32_16x16x32_bf16 v[48:51], v[198:201], v[222:225], v[48:51]
	v_mfma_f32_16x16x32_bf16 v[44:47], v[198:201], v[226:229], v[44:47]
	s_waitcnt vmcnt(0)
	s_barrier
	v_add_u32_e32 v164, v151, v150
	v_add_u32_e32 v134, v151, v148
	v_mfma_f32_16x16x32_bf16 v[40:43], v[202:205], v[214:217], v[40:43]
	ds_read_b128 v[152:155], v164 offset:32768
	ds_read_b128 v[156:159], v164 offset:34816
	v_mfma_f32_16x16x32_bf16 v[36:39], v[202:205], v[218:221], v[36:39]
	ds_read_b128 v[160:163], v164 offset:36864
	ds_read_b128 v[164:167], v164 offset:38912
	v_mfma_f32_16x16x32_bf16 v[32:35], v[202:205], v[222:225], v[32:35]
	ds_read_b128 v[168:171], v134 offset:0
	ds_read_b128 v[172:175], v134 offset:2048
	v_mfma_f32_16x16x32_bf16 v[28:31], v[202:205], v[226:229], v[28:31]
	ds_read_b128 v[176:179], v134 offset:4096
	ds_read_b128 v[180:183], v134 offset:6144
	s_add_i32 m0, s93, 0x10000
	v_mfma_f32_16x16x32_bf16 v[24:27], v[206:209], v[214:217], v[24:27]
	global_load_lds_dwordx4 v[128:129], off
	v_lshl_add_u64 v[128:129], v[128:129], 0, s[100:101]
	s_add_i32 m0, s93, 0x18000
	v_mfma_f32_16x16x32_bf16 v[20:23], v[206:209], v[218:221], v[20:23]
	global_load_lds_dwordx4 v[140:141], off
	v_lshl_add_u64 v[140:141], v[140:141], 0, s[100:101]
	s_add_i32 m0, s94, 0x10000
	v_mfma_f32_16x16x32_bf16 v[16:19], v[206:209], v[222:225], v[16:19]
	global_load_lds_dwordx4 v[130:131], off
	v_lshl_add_u64 v[130:131], v[130:131], 0, s[100:101]
	s_add_i32 m0, s94, 0x18000
	v_mfma_f32_16x16x32_bf16 v[12:15], v[206:209], v[226:229], v[12:15]
	global_load_lds_dwordx4 v[142:143], off
	v_lshl_add_u64 v[142:143], v[142:143], 0, s[100:101]
	s_add_i32 m0, s95, 0x10000
	v_mfma_f32_16x16x32_bf16 v[8:11], v[210:213], v[214:217], v[8:11]
	global_load_lds_dwordx4 v[136:137], off
	v_lshl_add_u64 v[136:137], v[136:137], 0, s[100:101]
	s_add_i32 m0, s95, 0x18000
	v_mfma_f32_16x16x32_bf16 v[4:7], v[210:213], v[218:221], v[4:7]
	global_load_lds_dwordx4 v[144:145], off
	v_lshl_add_u64 v[144:145], v[144:145], 0, s[100:101]
	s_add_i32 m0, s96, 0x10000
	v_mfma_f32_16x16x32_bf16 v[0:3], v[210:213], v[222:225], v[0:3]
	global_load_lds_dwordx4 v[138:139], off
	v_lshl_add_u64 v[138:139], v[138:139], 0, s[100:101]
	s_add_i32 m0, s96, 0x18000
	v_mfma_f32_16x16x32_bf16 v[88:91], v[210:213], v[226:229], v[88:91]
	global_load_lds_dwordx4 v[146:147], off
	v_lshl_add_u64 v[146:147], v[146:147], 0, s[100:101]
	s_movk_i32 s2, 0x100
.Lg_up_loop:
	ds_read_b128 v[198:201], v134 offset:8192
	ds_read_b128 v[202:205], v134 offset:10240
	ds_read_b128 v[206:209], v134 offset:12288
	ds_read_b128 v[210:213], v134 offset:14336
	s_waitcnt lgkmcnt(4)
	v_mfma_f32_16x16x32_bf16 v[124:127], v[168:171], v[152:155], v[124:127]
	v_mfma_f32_16x16x32_bf16 v[120:123], v[168:171], v[156:159], v[120:123]
	v_mfma_f32_16x16x32_bf16 v[116:119], v[168:171], v[160:163], v[116:119]
	v_mfma_f32_16x16x32_bf16 v[112:115], v[168:171], v[164:167], v[112:115]
	v_mfma_f32_16x16x32_bf16 v[108:111], v[172:175], v[152:155], v[108:111]
	v_mfma_f32_16x16x32_bf16 v[104:107], v[172:175], v[156:159], v[104:107]
	v_mfma_f32_16x16x32_bf16 v[100:103], v[172:175], v[160:163], v[100:103]
	v_mfma_f32_16x16x32_bf16 v[96:99], v[172:175], v[164:167], v[96:99]
	v_mfma_f32_16x16x32_bf16 v[92:95], v[176:179], v[152:155], v[92:95]
	v_mfma_f32_16x16x32_bf16 v[84:87], v[176:179], v[156:159], v[84:87]
	v_mfma_f32_16x16x32_bf16 v[80:83], v[176:179], v[160:163], v[80:83]
	v_mfma_f32_16x16x32_bf16 v[76:79], v[176:179], v[164:167], v[76:79]
	v_mfma_f32_16x16x32_bf16 v[72:75], v[180:183], v[152:155], v[72:75]
	v_mfma_f32_16x16x32_bf16 v[68:71], v[180:183], v[156:159], v[68:71]
	v_mfma_f32_16x16x32_bf16 v[64:67], v[180:183], v[160:163], v[64:67]
	v_mfma_f32_16x16x32_bf16 v[60:63], v[180:183], v[164:167], v[60:63]
	v_add_u32_e32 v180, v149, v150
	v_add_u32_e32 v134, v149, v148
	ds_read_b128 v[168:171], v180 offset:32768
	ds_read_b128 v[172:175], v180 offset:34816
	ds_read_b128 v[176:179], v180 offset:36864
	ds_read_b128 v[180:183], v180 offset:38912
	ds_read_b128 v[214:217], v134 offset:0
	ds_read_b128 v[218:221], v134 offset:2048
	ds_read_b128 v[222:225], v134 offset:4096
	ds_read_b128 v[226:229], v134 offset:6144
	s_waitcnt lgkmcnt(8)
	v_mfma_f32_16x16x32_bf16 v[56:59], v[198:201], v[152:155], v[56:59]
	v_mfma_f32_16x16x32_bf16 v[52:55], v[198:201], v[156:159], v[52:55]
	v_mfma_f32_16x16x32_bf16 v[48:51], v[198:201], v[160:163], v[48:51]
	v_mfma_f32_16x16x32_bf16 v[44:47], v[198:201], v[164:167], v[44:47]
	v_mfma_f32_16x16x32_bf16 v[40:43], v[202:205], v[152:155], v[40:43]
	v_mfma_f32_16x16x32_bf16 v[36:39], v[202:205], v[156:159], v[36:39]
	v_mfma_f32_16x16x32_bf16 v[32:35], v[202:205], v[160:163], v[32:35]
	v_mfma_f32_16x16x32_bf16 v[28:31], v[202:205], v[164:167], v[28:31]
	v_mfma_f32_16x16x32_bf16 v[24:27], v[206:209], v[152:155], v[24:27]
	v_mfma_f32_16x16x32_bf16 v[20:23], v[206:209], v[156:159], v[20:23]
	v_mfma_f32_16x16x32_bf16 v[16:19], v[206:209], v[160:163], v[16:19]
	v_mfma_f32_16x16x32_bf16 v[12:15], v[206:209], v[164:167], v[12:15]
	v_mfma_f32_16x16x32_bf16 v[8:11], v[210:213], v[152:155], v[8:11]
	v_mfma_f32_16x16x32_bf16 v[4:7], v[210:213], v[156:159], v[4:7]
	v_mfma_f32_16x16x32_bf16 v[0:3], v[210:213], v[160:163], v[0:3]
	v_mfma_f32_16x16x32_bf16 v[88:91], v[210:213], v[164:167], v[88:91]
	ds_read_b128 v[152:155], v134 offset:8192
	ds_read_b128 v[156:159], v134 offset:10240
	ds_read_b128 v[160:163], v134 offset:12288
	ds_read_b128 v[164:167], v134 offset:14336
	s_waitcnt lgkmcnt(4)
	v_mfma_f32_16x16x32_bf16 v[124:127], v[214:217], v[168:171], v[124:127]
	v_mfma_f32_16x16x32_bf16 v[120:123], v[214:217], v[172:175], v[120:123]
	v_mfma_f32_16x16x32_bf16 v[116:119], v[214:217], v[176:179], v[116:119]
	v_mfma_f32_16x16x32_bf16 v[112:115], v[214:217], v[180:183], v[112:115]
	v_mfma_f32_16x16x32_bf16 v[108:111], v[218:221], v[168:171], v[108:111]
	v_mfma_f32_16x16x32_bf16 v[104:107], v[218:221], v[172:175], v[104:107]
	v_mfma_f32_16x16x32_bf16 v[100:103], v[218:221], v[176:179], v[100:103]
	v_mfma_f32_16x16x32_bf16 v[96:99], v[218:221], v[180:183], v[96:99]
	v_mfma_f32_16x16x32_bf16 v[92:95], v[222:225], v[168:171], v[92:95]
	v_mfma_f32_16x16x32_bf16 v[84:87], v[222:225], v[172:175], v[84:87]
	v_mfma_f32_16x16x32_bf16 v[80:83], v[222:225], v[176:179], v[80:83]
	v_mfma_f32_16x16x32_bf16 v[76:79], v[222:225], v[180:183], v[76:79]
	v_mfma_f32_16x16x32_bf16 v[72:75], v[226:229], v[168:171], v[72:75]
	v_mfma_f32_16x16x32_bf16 v[68:71], v[226:229], v[172:175], v[68:71]
	v_mfma_f32_16x16x32_bf16 v[64:67], v[226:229], v[176:179], v[64:67]
	v_mfma_f32_16x16x32_bf16 v[60:63], v[226:229], v[180:183], v[60:63]
	s_waitcnt lgkmcnt(0)
	v_mfma_f32_16x16x32_bf16 v[56:59], v[152:155], v[168:171], v[56:59]
	v_mfma_f32_16x16x32_bf16 v[52:55], v[152:155], v[172:175], v[52:55]
	v_mfma_f32_16x16x32_bf16 v[48:51], v[152:155], v[176:179], v[48:51]
	v_mfma_f32_16x16x32_bf16 v[44:47], v[152:155], v[180:183], v[44:47]
	s_waitcnt vmcnt(0)
	s_barrier
	v_add3_u32 v210, v151, v150, s99
	v_add3_u32 v134, v151, v148, s99
	v_mfma_f32_16x16x32_bf16 v[40:43], v[156:159], v[168:171], v[40:43]
	ds_read_b128 v[198:201], v210 offset:32768
	ds_read_b128 v[202:205], v210 offset:34816
	v_mfma_f32_16x16x32_bf16 v[36:39], v[156:159], v[172:175], v[36:39]
	ds_read_b128 v[206:209], v210 offset:36864
	ds_read_b128 v[210:213], v210 offset:38912
	v_mfma_f32_16x16x32_bf16 v[32:35], v[156:159], v[176:179], v[32:35]
	ds_read_b128 v[214:217], v134 offset:0
	ds_read_b128 v[218:221], v134 offset:2048
	v_mfma_f32_16x16x32_bf16 v[28:31], v[156:159], v[180:183], v[28:31]
	ds_read_b128 v[222:225], v134 offset:4096
	ds_read_b128 v[226:229], v134 offset:6144
	s_mov_b32 m0, s93
	v_mfma_f32_16x16x32_bf16 v[24:27], v[160:163], v[168:171], v[24:27]
	global_load_lds_dwordx4 v[128:129], off
	v_lshl_add_u64 v[128:129], v[128:129], 0, s[100:101]
	s_add_i32 m0, s93, 0x8000
	v_mfma_f32_16x16x32_bf16 v[20:23], v[160:163], v[172:175], v[20:23]
	global_load_lds_dwordx4 v[140:141], off
	v_lshl_add_u64 v[140:141], v[140:141], 0, s[100:101]
	s_mov_b32 m0, s94
	v_mfma_f32_16x16x32_bf16 v[16:19], v[160:163], v[176:179], v[16:19]
	global_load_lds_dwordx4 v[130:131], off
	v_lshl_add_u64 v[130:131], v[130:131], 0, s[100:101]
	s_add_i32 m0, s94, 0x8000
	v_mfma_f32_16x16x32_bf16 v[12:15], v[160:163], v[180:183], v[12:15]
	global_load_lds_dwordx4 v[142:143], off
	v_lshl_add_u64 v[142:143], v[142:143], 0, s[100:101]
	s_mov_b32 m0, s95
	v_mfma_f32_16x16x32_bf16 v[8:11], v[164:167], v[168:171], v[8:11]
	global_load_lds_dwordx4 v[136:137], off
	v_lshl_add_u64 v[136:137], v[136:137], 0, s[100:101]
	s_add_i32 m0, s95, 0x8000
	v_mfma_f32_16x16x32_bf16 v[4:7], v[164:167], v[172:175], v[4:7]
	global_load_lds_dwordx4 v[144:145], off
	v_lshl_add_u64 v[144:145], v[144:145], 0, s[100:101]
	s_mov_b32 m0, s96
	v_mfma_f32_16x16x32_bf16 v[0:3], v[164:167], v[176:179], v[0:3]
	global_load_lds_dwordx4 v[138:139], off
	v_lshl_add_u64 v[138:139], v[138:139], 0, s[100:101]
	s_add_i32 m0, s96, 0x8000
	v_mfma_f32_16x16x32_bf16 v[88:91], v[164:167], v[180:183], v[88:91]
	global_load_lds_dwordx4 v[146:147], off
	v_lshl_add_u64 v[146:147], v[146:147], 0, s[100:101]
	ds_read_b128 v[152:155], v134 offset:8192
	ds_read_b128 v[156:159], v134 offset:10240
	ds_read_b128 v[160:163], v134 offset:12288
	ds_read_b128 v[164:167], v134 offset:14336
	s_waitcnt lgkmcnt(4)
	v_mfma_f32_16x16x32_bf16 v[124:127], v[214:217], v[198:201], v[124:127]
	v_mfma_f32_16x16x32_bf16 v[120:123], v[214:217], v[202:205], v[120:123]
	v_mfma_f32_16x16x32_bf16 v[116:119], v[214:217], v[206:209], v[116:119]
	v_mfma_f32_16x16x32_bf16 v[112:115], v[214:217], v[210:213], v[112:115]
	v_mfma_f32_16x16x32_bf16 v[108:111], v[218:221], v[198:201], v[108:111]
	v_mfma_f32_16x16x32_bf16 v[104:107], v[218:221], v[202:205], v[104:107]
	v_mfma_f32_16x16x32_bf16 v[100:103], v[218:221], v[206:209], v[100:103]
	v_mfma_f32_16x16x32_bf16 v[96:99], v[218:221], v[210:213], v[96:99]
	v_mfma_f32_16x16x32_bf16 v[92:95], v[222:225], v[198:201], v[92:95]
	v_mfma_f32_16x16x32_bf16 v[84:87], v[222:225], v[202:205], v[84:87]
	v_mfma_f32_16x16x32_bf16 v[80:83], v[222:225], v[206:209], v[80:83]
	v_mfma_f32_16x16x32_bf16 v[76:79], v[222:225], v[210:213], v[76:79]
	v_mfma_f32_16x16x32_bf16 v[72:75], v[226:229], v[198:201], v[72:75]
	v_mfma_f32_16x16x32_bf16 v[68:71], v[226:229], v[202:205], v[68:71]
	v_mfma_f32_16x16x32_bf16 v[64:67], v[226:229], v[206:209], v[64:67]
	v_mfma_f32_16x16x32_bf16 v[60:63], v[226:229], v[210:213], v[60:63]
	v_add3_u32 v226, v149, v150, s99
	v_add3_u32 v134, v149, v148, s99
	ds_read_b128 v[214:217], v226 offset:32768
	ds_read_b128 v[218:221], v226 offset:34816
	ds_read_b128 v[222:225], v226 offset:36864
	ds_read_b128 v[226:229], v226 offset:38912
	ds_read_b128 v[168:171], v134 offset:0
	ds_read_b128 v[172:175], v134 offset:2048
	ds_read_b128 v[176:179], v134 offset:4096
	ds_read_b128 v[180:183], v134 offset:6144
	s_waitcnt lgkmcnt(8)
	v_mfma_f32_16x16x32_bf16 v[56:59], v[152:155], v[198:201], v[56:59]
	v_mfma_f32_16x16x32_bf16 v[52:55], v[152:155], v[202:205], v[52:55]
	v_mfma_f32_16x16x32_bf16 v[48:51], v[152:155], v[206:209], v[48:51]
	v_mfma_f32_16x16x32_bf16 v[44:47], v[152:155], v[210:213], v[44:47]
	v_mfma_f32_16x16x32_bf16 v[40:43], v[156:159], v[198:201], v[40:43]
	v_mfma_f32_16x16x32_bf16 v[36:39], v[156:159], v[202:205], v[36:39]
	v_mfma_f32_16x16x32_bf16 v[32:35], v[156:159], v[206:209], v[32:35]
	v_mfma_f32_16x16x32_bf16 v[28:31], v[156:159], v[210:213], v[28:31]
	v_mfma_f32_16x16x32_bf16 v[24:27], v[160:163], v[198:201], v[24:27]
	v_mfma_f32_16x16x32_bf16 v[20:23], v[160:163], v[202:205], v[20:23]
	v_mfma_f32_16x16x32_bf16 v[16:19], v[160:163], v[206:209], v[16:19]
	v_mfma_f32_16x16x32_bf16 v[12:15], v[160:163], v[210:213], v[12:15]
	v_mfma_f32_16x16x32_bf16 v[8:11], v[164:167], v[198:201], v[8:11]
	v_mfma_f32_16x16x32_bf16 v[4:7], v[164:167], v[202:205], v[4:7]
	v_mfma_f32_16x16x32_bf16 v[0:3], v[164:167], v[206:209], v[0:3]
	v_mfma_f32_16x16x32_bf16 v[88:91], v[164:167], v[210:213], v[88:91]
	ds_read_b128 v[198:201], v134 offset:8192
	ds_read_b128 v[202:205], v134 offset:10240
	ds_read_b128 v[206:209], v134 offset:12288
	ds_read_b128 v[210:213], v134 offset:14336
	s_waitcnt lgkmcnt(4)
	v_mfma_f32_16x16x32_bf16 v[124:127], v[168:171], v[214:217], v[124:127]
	v_mfma_f32_16x16x32_bf16 v[120:123], v[168:171], v[218:221], v[120:123]
	v_mfma_f32_16x16x32_bf16 v[116:119], v[168:171], v[222:225], v[116:119]
	v_mfma_f32_16x16x32_bf16 v[112:115], v[168:171], v[226:229], v[112:115]
	v_mfma_f32_16x16x32_bf16 v[108:111], v[172:175], v[214:217], v[108:111]
	v_mfma_f32_16x16x32_bf16 v[104:107], v[172:175], v[218:221], v[104:107]
	v_mfma_f32_16x16x32_bf16 v[100:103], v[172:175], v[222:225], v[100:103]
	v_mfma_f32_16x16x32_bf16 v[96:99], v[172:175], v[226:229], v[96:99]
	v_mfma_f32_16x16x32_bf16 v[92:95], v[176:179], v[214:217], v[92:95]
	v_mfma_f32_16x16x32_bf16 v[84:87], v[176:179], v[218:221], v[84:87]
	v_mfma_f32_16x16x32_bf16 v[80:83], v[176:179], v[222:225], v[80:83]
	v_mfma_f32_16x16x32_bf16 v[76:79], v[176:179], v[226:229], v[76:79]
	v_mfma_f32_16x16x32_bf16 v[72:75], v[180:183], v[214:217], v[72:75]
	v_mfma_f32_16x16x32_bf16 v[68:71], v[180:183], v[218:221], v[68:71]
	v_mfma_f32_16x16x32_bf16 v[64:67], v[180:183], v[222:225], v[64:67]
	v_mfma_f32_16x16x32_bf16 v[60:63], v[180:183], v[226:229], v[60:63]
	s_waitcnt lgkmcnt(0)
	v_mfma_f32_16x16x32_bf16 v[56:59], v[198:201], v[214:217], v[56:59]
	v_mfma_f32_16x16x32_bf16 v[52:55], v[198:201], v[218:221], v[52:55]
	v_mfma_f32_16x16x32_bf16 v[48:51], v[198:201], v[222:225], v[48:51]
	v_mfma_f32_16x16x32_bf16 v[44:47], v[198:201], v[226:229], v[44:47]
	s_waitcnt vmcnt(0)
	s_barrier
	v_add_u32_e32 v164, v151, v150
	v_add_u32_e32 v134, v151, v148
	v_mfma_f32_16x16x32_bf16 v[40:43], v[202:205], v[214:217], v[40:43]
	ds_read_b128 v[152:155], v164 offset:32768
	ds_read_b128 v[156:159], v164 offset:34816
	v_mfma_f32_16x16x32_bf16 v[36:39], v[202:205], v[218:221], v[36:39]
	ds_read_b128 v[160:163], v164 offset:36864
	ds_read_b128 v[164:167], v164 offset:38912
	v_mfma_f32_16x16x32_bf16 v[32:35], v[202:205], v[222:225], v[32:35]
	ds_read_b128 v[168:171], v134 offset:0
	ds_read_b128 v[172:175], v134 offset:2048
	v_mfma_f32_16x16x32_bf16 v[28:31], v[202:205], v[226:229], v[28:31]
	ds_read_b128 v[176:179], v134 offset:4096
	ds_read_b128 v[180:183], v134 offset:6144
	s_add_i32 m0, s93, 0x10000
	v_mfma_f32_16x16x32_bf16 v[24:27], v[206:209], v[214:217], v[24:27]
	global_load_lds_dwordx4 v[128:129], off
	v_lshl_add_u64 v[128:129], v[128:129], 0, s[100:101]
	s_add_i32 m0, s93, 0x18000
	v_mfma_f32_16x16x32_bf16 v[20:23], v[206:209], v[218:221], v[20:23]
	global_load_lds_dwordx4 v[140:141], off
	v_lshl_add_u64 v[140:141], v[140:141], 0, s[100:101]
	s_add_i32 m0, s94, 0x10000
	v_mfma_f32_16x16x32_bf16 v[16:19], v[206:209], v[222:225], v[16:19]
	global_load_lds_dwordx4 v[130:131], off
	v_lshl_add_u64 v[130:131], v[130:131], 0, s[100:101]
	s_add_i32 m0, s94, 0x18000
	v_mfma_f32_16x16x32_bf16 v[12:15], v[206:209], v[226:229], v[12:15]
	global_load_lds_dwordx4 v[142:143], off
	v_lshl_add_u64 v[142:143], v[142:143], 0, s[100:101]
	s_add_i32 m0, s95, 0x10000
	v_mfma_f32_16x16x32_bf16 v[8:11], v[210:213], v[214:217], v[8:11]
	global_load_lds_dwordx4 v[136:137], off
	v_lshl_add_u64 v[136:137], v[136:137], 0, s[100:101]
	s_add_i32 m0, s95, 0x18000
	v_mfma_f32_16x16x32_bf16 v[4:7], v[210:213], v[218:221], v[4:7]
	global_load_lds_dwordx4 v[144:145], off
	v_lshl_add_u64 v[144:145], v[144:145], 0, s[100:101]
	s_add_i32 m0, s96, 0x10000
	v_mfma_f32_16x16x32_bf16 v[0:3], v[210:213], v[222:225], v[0:3]
	global_load_lds_dwordx4 v[138:139], off
	v_lshl_add_u64 v[138:139], v[138:139], 0, s[100:101]
	s_add_i32 m0, s96, 0x18000
	v_mfma_f32_16x16x32_bf16 v[88:91], v[210:213], v[226:229], v[88:91]
	global_load_lds_dwordx4 v[146:147], off
	v_lshl_add_u64 v[146:147], v[146:147], 0, s[100:101]
	s_add_u32 s2, s2, 0x100
	s_cmpk_lg_i32 s2, 0x700
	s_cbranch_scc1 .Lg_up_loop
	ds_read_b128 v[198:201], v134 offset:8192
	ds_read_b128 v[202:205], v134 offset:10240
	ds_read_b128 v[206:209], v134 offset:12288
	ds_read_b128 v[210:213], v134 offset:14336
	s_waitcnt lgkmcnt(4)
	v_mfma_f32_16x16x32_bf16 v[124:127], v[168:171], v[152:155], v[124:127]
	v_mfma_f32_16x16x32_bf16 v[120:123], v[168:171], v[156:159], v[120:123]
	v_mfma_f32_16x16x32_bf16 v[116:119], v[168:171], v[160:163], v[116:119]
	v_mfma_f32_16x16x32_bf16 v[112:115], v[168:171], v[164:167], v[112:115]
	v_mfma_f32_16x16x32_bf16 v[108:111], v[172:175], v[152:155], v[108:111]
	v_mfma_f32_16x16x32_bf16 v[104:107], v[172:175], v[156:159], v[104:107]
	v_mfma_f32_16x16x32_bf16 v[100:103], v[172:175], v[160:163], v[100:103]
	v_mfma_f32_16x16x32_bf16 v[96:99], v[172:175], v[164:167], v[96:99]
	v_mfma_f32_16x16x32_bf16 v[92:95], v[176:179], v[152:155], v[92:95]
	v_mfma_f32_16x16x32_bf16 v[84:87], v[176:179], v[156:159], v[84:87]
	v_mfma_f32_16x16x32_bf16 v[80:83], v[176:179], v[160:163], v[80:83]
	v_mfma_f32_16x16x32_bf16 v[76:79], v[176:179], v[164:167], v[76:79]
	v_mfma_f32_16x16x32_bf16 v[72:75], v[180:183], v[152:155], v[72:75]
	v_mfma_f32_16x16x32_bf16 v[68:71], v[180:183], v[156:159], v[68:71]
	v_mfma_f32_16x16x32_bf16 v[64:67], v[180:183], v[160:163], v[64:67]
	v_mfma_f32_16x16x32_bf16 v[60:63], v[180:183], v[164:167], v[60:63]
	v_add_u32_e32 v180, v149, v150
	v_add_u32_e32 v134, v149, v148
	ds_read_b128 v[168:171], v180 offset:32768
	ds_read_b128 v[172:175], v180 offset:34816
	ds_read_b128 v[176:179], v180 offset:36864
	ds_read_b128 v[180:183], v180 offset:38912
	ds_read_b128 v[214:217], v134 offset:0
	ds_read_b128 v[218:221], v134 offset:2048
	ds_read_b128 v[222:225], v134 offset:4096
	ds_read_b128 v[226:229], v134 offset:6144
	s_waitcnt lgkmcnt(8)
	v_mfma_f32_16x16x32_bf16 v[56:59], v[198:201], v[152:155], v[56:59]
	v_mfma_f32_16x16x32_bf16 v[52:55], v[198:201], v[156:159], v[52:55]
	v_mfma_f32_16x16x32_bf16 v[48:51], v[198:201], v[160:163], v[48:51]
	v_mfma_f32_16x16x32_bf16 v[44:47], v[198:201], v[164:167], v[44:47]
	v_mfma_f32_16x16x32_bf16 v[40:43], v[202:205], v[152:155], v[40:43]
	v_mfma_f32_16x16x32_bf16 v[36:39], v[202:205], v[156:159], v[36:39]
	v_mfma_f32_16x16x32_bf16 v[32:35], v[202:205], v[160:163], v[32:35]
	v_mfma_f32_16x16x32_bf16 v[28:31], v[202:205], v[164:167], v[28:31]
	v_mfma_f32_16x16x32_bf16 v[24:27], v[206:209], v[152:155], v[24:27]
	v_mfma_f32_16x16x32_bf16 v[20:23], v[206:209], v[156:159], v[20:23]
	v_mfma_f32_16x16x32_bf16 v[16:19], v[206:209], v[160:163], v[16:19]
	v_mfma_f32_16x16x32_bf16 v[12:15], v[206:209], v[164:167], v[12:15]
	v_mfma_f32_16x16x32_bf16 v[8:11], v[210:213], v[152:155], v[8:11]
	v_mfma_f32_16x16x32_bf16 v[4:7], v[210:213], v[156:159], v[4:7]
	v_mfma_f32_16x16x32_bf16 v[0:3], v[210:213], v[160:163], v[0:3]
	v_mfma_f32_16x16x32_bf16 v[88:91], v[210:213], v[164:167], v[88:91]
	ds_read_b128 v[152:155], v134 offset:8192
	ds_read_b128 v[156:159], v134 offset:10240
	ds_read_b128 v[160:163], v134 offset:12288
	ds_read_b128 v[164:167], v134 offset:14336
	s_waitcnt lgkmcnt(4)
	v_mfma_f32_16x16x32_bf16 v[124:127], v[214:217], v[168:171], v[124:127]
	v_mfma_f32_16x16x32_bf16 v[120:123], v[214:217], v[172:175], v[120:123]
	v_mfma_f32_16x16x32_bf16 v[116:119], v[214:217], v[176:179], v[116:119]
	v_mfma_f32_16x16x32_bf16 v[112:115], v[214:217], v[180:183], v[112:115]
	v_mfma_f32_16x16x32_bf16 v[108:111], v[218:221], v[168:171], v[108:111]
	v_mfma_f32_16x16x32_bf16 v[104:107], v[218:221], v[172:175], v[104:107]
	v_mfma_f32_16x16x32_bf16 v[100:103], v[218:221], v[176:179], v[100:103]
	v_mfma_f32_16x16x32_bf16 v[96:99], v[218:221], v[180:183], v[96:99]
	v_mfma_f32_16x16x32_bf16 v[92:95], v[222:225], v[168:171], v[92:95]
	v_mfma_f32_16x16x32_bf16 v[84:87], v[222:225], v[172:175], v[84:87]
	v_mfma_f32_16x16x32_bf16 v[80:83], v[222:225], v[176:179], v[80:83]
	v_mfma_f32_16x16x32_bf16 v[76:79], v[222:225], v[180:183], v[76:79]
	v_mfma_f32_16x16x32_bf16 v[72:75], v[226:229], v[168:171], v[72:75]
	v_mfma_f32_16x16x32_bf16 v[68:71], v[226:229], v[172:175], v[68:71]
	v_mfma_f32_16x16x32_bf16 v[64:67], v[226:229], v[176:179], v[64:67]
	v_mfma_f32_16x16x32_bf16 v[60:63], v[226:229], v[180:183], v[60:63]
	s_waitcnt lgkmcnt(0)
	v_mfma_f32_16x16x32_bf16 v[56:59], v[152:155], v[168:171], v[56:59]
	v_mfma_f32_16x16x32_bf16 v[52:55], v[152:155], v[172:175], v[52:55]
	v_mfma_f32_16x16x32_bf16 v[48:51], v[152:155], v[176:179], v[48:51]
	v_mfma_f32_16x16x32_bf16 v[44:47], v[152:155], v[180:183], v[44:47]
	s_waitcnt vmcnt(0)
	s_barrier
	v_lshlrev_b32_e32 v254, 3, v184
	v_and_b32_e32 v254, 0x78, v254
	v_lshl_or_b32 v254, s44, 7, v254
	v_lshlrev_b32_e32 v254, 2, v254
	v_add_u32_e32 v222, 0x2c00, v254
	v_add_u32_e32 v223, 0x5800, v254
	global_load_dwordx4 v[234:237], v254, s[10:11]
	global_load_dwordx4 v[230:233], v254, s[10:11] offset:16
	global_load_dwordx4 v[238:241], v222, s[10:11]
	global_load_dwordx4 v[242:245], v222, s[10:11] offset:16
	global_load_dwordx4 v[246:249], v223, s[10:11]
	global_load_dwordx4 v[250:253], v223, s[10:11] offset:16
	global_load_dwordx4 v[214:217], v254, s[12:13] offset:16
	global_load_dwordx4 v[218:221], v254, s[12:13]
	v_mfma_f32_16x16x32_bf16 v[40:43], v[156:159], v[168:171], v[40:43]
	v_mfma_f32_16x16x32_bf16 v[36:39], v[156:159], v[172:175], v[36:39]
	v_mfma_f32_16x16x32_bf16 v[32:35], v[156:159], v[176:179], v[32:35]
	v_mfma_f32_16x16x32_bf16 v[28:31], v[156:159], v[180:183], v[28:31]
	v_mfma_f32_16x16x32_bf16 v[24:27], v[160:163], v[168:171], v[24:27]
	v_mfma_f32_16x16x32_bf16 v[20:23], v[160:163], v[172:175], v[20:23]
	v_mfma_f32_16x16x32_bf16 v[16:19], v[160:163], v[176:179], v[16:19]
	v_mfma_f32_16x16x32_bf16 v[12:15], v[160:163], v[180:183], v[12:15]
	v_mfma_f32_16x16x32_bf16 v[8:11], v[164:167], v[168:171], v[8:11]
	v_mfma_f32_16x16x32_bf16 v[4:7], v[164:167], v[172:175], v[4:7]
	v_mfma_f32_16x16x32_bf16 v[0:3], v[164:167], v[176:179], v[0:3]
	v_mfma_f32_16x16x32_bf16 v[88:91], v[164:167], v[180:183], v[88:91]
	s_movk_i32 s2, 0x780
	s_mov_b32 s97, 0xf0000
	v_add3_u32 v134, v148, v151, s75
	ds_read_b128 v[128:131], v134 offset:14336
	ds_read_b128 v[136:139], v134 offset:12288
	ds_read_b128 v[140:143], v134 offset:10240
	ds_read_b128 v[144:147], v134 offset:8192
	ds_read_b128 v[152:155], v134 offset:6144
	ds_read_b128 v[156:159], v134 offset:4096
	ds_read_b128 v[160:163], v134 offset:2048
	ds_read_b128 v[164:167], v134
	v_add3_u32 v134, v150, v151, s63
	ds_read_b128 v[168:171], v134 offset:6144
	ds_read_b128 v[172:175], v134 offset:4096
	ds_read_b128 v[176:179], v134 offset:2048
	ds_read_b128 v[180:183], v134
	s_waitcnt lgkmcnt(0)
	v_mfma_f32_16x16x32_bf16 v[124:127], v[164:167], v[180:183], v[124:127]
	v_mfma_f32_16x16x32_bf16 v[120:123], v[164:167], v[176:179], v[120:123]
	v_mfma_f32_16x16x32_bf16 v[116:119], v[164:167], v[172:175], v[116:119]
	v_mfma_f32_16x16x32_bf16 v[112:115], v[164:167], v[168:171], v[112:115]
	v_mfma_f32_16x16x32_bf16 v[108:111], v[160:163], v[180:183], v[108:111]
	v_mfma_f32_16x16x32_bf16 v[104:107], v[160:163], v[176:179], v[104:107]
	v_mfma_f32_16x16x32_bf16 v[100:103], v[160:163], v[172:175], v[100:103]
	v_mfma_f32_16x16x32_bf16 v[96:99], v[160:163], v[168:171], v[96:99]
	v_mfma_f32_16x16x32_bf16 v[92:95], v[156:159], v[180:183], v[92:95]
	v_mfma_f32_16x16x32_bf16 v[84:87], v[156:159], v[176:179], v[84:87]
	v_mfma_f32_16x16x32_bf16 v[80:83], v[156:159], v[172:175], v[80:83]
	v_mfma_f32_16x16x32_bf16 v[76:79], v[156:159], v[168:171], v[76:79]
	v_mfma_f32_16x16x32_bf16 v[72:75], v[152:155], v[180:183], v[72:75]
	v_mfma_f32_16x16x32_bf16 v[68:71], v[152:155], v[176:179], v[68:71]
	v_mfma_f32_16x16x32_bf16 v[64:67], v[152:155], v[172:175], v[64:67]
	v_mfma_f32_16x16x32_bf16 v[60:63], v[152:155], v[168:171], v[60:63]
	v_add3_u32 v134, v150, v149, s63
	ds_read_b128 v[150:153], v134
	ds_read_b128 v[154:157], v134 offset:2048
	ds_read_b128 v[158:161], v134 offset:4096
	ds_read_b128 v[162:165], v134 offset:6144
	v_add3_u32 v134, v148, v149, s75
	ds_read_b128 v[198:201], v134
	ds_read_b128 v[202:205], v134 offset:2048
	ds_read_b128 v[206:209], v134 offset:4096
	ds_read_b128 v[210:213], v134 offset:6144
	v_mfma_f32_16x16x32_bf16 v[44:47], v[144:147], v[168:171], v[44:47]
	v_mfma_f32_16x16x32_bf16 v[40:43], v[140:143], v[180:183], v[40:43]
	v_mfma_f32_16x16x32_bf16 v[28:31], v[140:143], v[168:171], v[28:31]
	v_mfma_f32_16x16x32_bf16 v[24:27], v[136:139], v[180:183], v[24:27]
	v_mfma_f32_16x16x32_bf16 v[20:23], v[136:139], v[176:179], v[20:23]
	v_mfma_f32_16x16x32_bf16 v[16:19], v[136:139], v[172:175], v[16:19]
	v_mfma_f32_16x16x32_bf16 v[12:15], v[136:139], v[168:171], v[12:15]
	v_mfma_f32_16x16x32_bf16 v[8:11], v[128:131], v[180:183], v[8:11]
	v_mfma_f32_16x16x32_bf16 v[4:7], v[128:131], v[176:179], v[4:7]
	v_mfma_f32_16x16x32_bf16 v[0:3], v[128:131], v[172:175], v[0:3]
	v_mfma_f32_16x16x32_bf16 v[56:59], v[144:147], v[180:183], v[56:59]
	v_mfma_f32_16x16x32_bf16 v[52:55], v[144:147], v[176:179], v[52:55]
	v_mfma_f32_16x16x32_bf16 v[48:51], v[144:147], v[172:175], v[48:51]
	v_mfma_f32_16x16x32_bf16 v[36:39], v[140:143], v[176:179], v[36:39]
	v_mfma_f32_16x16x32_bf16 v[32:35], v[140:143], v[172:175], v[32:35]
	v_mfma_f32_16x16x32_bf16 v[88:91], v[128:131], v[168:171], v[88:91]
	ds_read_b128 v[128:131], v134 offset:8192
	ds_read_b128 v[136:139], v134 offset:10240
	ds_read_b128 v[140:143], v134 offset:12288
	ds_read_b128 v[144:147], v134 offset:14336
	s_waitcnt lgkmcnt(0)
	v_mfma_f32_16x16x32_bf16 v[124:127], v[198:201], v[150:153], v[124:127]
	v_mfma_f32_16x16x32_bf16 v[120:123], v[198:201], v[154:157], v[120:123]
	v_mfma_f32_16x16x32_bf16 v[116:119], v[198:201], v[158:161], v[116:119]
	v_mfma_f32_16x16x32_bf16 v[112:115], v[198:201], v[162:165], v[112:115]
	v_mfma_f32_16x16x32_bf16 v[108:111], v[202:205], v[150:153], v[108:111]
	v_mfma_f32_16x16x32_bf16 v[104:107], v[202:205], v[154:157], v[104:107]
	v_mfma_f32_16x16x32_bf16 v[100:103], v[202:205], v[158:161], v[100:103]
	v_mfma_f32_16x16x32_bf16 v[96:99], v[202:205], v[162:165], v[96:99]
	v_mfma_f32_16x16x32_bf16 v[92:95], v[206:209], v[150:153], v[92:95]
	v_mfma_f32_16x16x32_bf16 v[84:87], v[206:209], v[154:157], v[84:87]
	v_mfma_f32_16x16x32_bf16 v[80:83], v[206:209], v[158:161], v[80:83]
	v_mfma_f32_16x16x32_bf16 v[76:79], v[206:209], v[162:165], v[76:79]
	v_mfma_f32_16x16x32_bf16 v[72:75], v[210:213], v[150:153], v[72:75]
	v_mfma_f32_16x16x32_bf16 v[68:71], v[210:213], v[154:157], v[68:71]
	v_mfma_f32_16x16x32_bf16 v[64:67], v[210:213], v[158:161], v[64:67]
	v_mfma_f32_16x16x32_bf16 v[60:63], v[210:213], v[162:165], v[60:63]
	v_mov_b32_e32 v148, v184
	v_mfma_f32_16x16x32_bf16 v[24:27], v[140:143], v[150:153], v[24:27]
	s_waitcnt lgkmcnt(0)
	s_barrier
	v_mfma_f32_16x16x32_bf16 v[8:11], v[144:147], v[150:153], v[8:11]
	s_nop 5
	v_cvt_pk_bf16_f32 v24, v24, v25
	v_lshrrev_b32_e32 v134, 8, v148
	v_mul_i32_i24_e32 v134, 0x11000, v134
	v_lshrrev_b32_e32 v166, 1, v148
	v_and_b32_e32 v149, 0xcf, v148
	v_and_or_b32 v134, v166, 24, v134
	v_mfma_f32_16x16x32_bf16 v[56:59], v[128:131], v[150:153], v[56:59]
	v_cvt_pk_bf16_f32 v25, v26, v27
	v_cvt_pk_bf16_f32 v8, v8, v9
	v_cvt_pk_bf16_f32 v9, v10, v11
	v_mfma_f32_16x16x32_bf16 v[52:55], v[128:131], v[154:157], v[52:55]
	s_mov_b64 s[2:3], 0x2c00
	s_nop 2
	v_cvt_pk_bf16_f32 v56, v56, v57
	v_cvt_pk_bf16_f32 v57, v58, v59
	v_mfma_f32_16x16x32_bf16 v[48:51], v[128:131], v[158:161], v[48:51]
	v_cvt_pk_bf16_f32 v124, v124, v125
	v_cvt_pk_bf16_f32 v125, v126, v127
	v_cvt_pk_bf16_f32 v108, v108, v109
	v_mfma_f32_16x16x32_bf16 v[44:47], v[128:131], v[162:165], v[44:47]
	v_mad_u32_u24 v128, v149, s51, v134
	ds_write2_b64 v128, v[24:25], v[8:9] offset0:24 offset1:28
	v_cvt_pk_bf16_f32 v24, v52, v53
	v_mfma_f32_16x16x32_bf16 v[40:43], v[136:139], v[150:153], v[40:43]
	v_cvt_pk_bf16_f32 v25, v54, v55
	v_cvt_pk_bf16_f32 v109, v110, v111
	v_cvt_pk_bf16_f32 v92, v92, v93
	v_mfma_f32_16x16x32_bf16 v[8:11], v[140:143], v[154:157], v[20:23]
	v_cvt_pk_bf16_f32 v93, v94, v95
	s_nop 2
	v_cvt_pk_bf16_f32 v40, v40, v41
	v_cvt_pk_bf16_f32 v41, v42, v43
	v_mfma_f32_16x16x32_bf16 v[4:7], v[144:147], v[154:157], v[4:7]
	ds_write2_b64 v128, v[56:57], v[40:41] offset0:16 offset1:20
	v_add_u32_e32 v40, 0x1000, v128
	v_cvt_pk_bf16_f32 v8, v8, v9
	v_mfma_f32_16x16x32_bf16 v[32:35], v[136:139], v[158:161], v[32:35]
	v_cvt_pk_bf16_f32 v9, v10, v11
	s_nop 2
	v_cvt_pk_bf16_f32 v4, v4, v5
	v_cvt_pk_bf16_f32 v5, v6, v7
	v_mfma_f32_16x16x32_bf16 v[16:19], v[140:143], v[158:161], v[16:19]
	ds_write2_b64 v40, v[8:9], v[4:5] offset0:56 offset1:60
	v_cvt_pk_bf16_f32 v4, v116, v117
	v_cvt_pk_bf16_f32 v5, v118, v119
	v_mfma_f32_16x16x32_bf16 v[0:3], v[144:147], v[158:161], v[0:3]
	v_cvt_pk_bf16_f32 v6, v100, v101
	v_cvt_pk_bf16_f32 v7, v102, v103
	v_add_u32_e32 v8, 0x2000, v128
	v_cvt_pk_bf16_f32 v20, v120, v121
	v_cvt_pk_bf16_f32 v21, v122, v123
	v_cvt_pk_bf16_f32 v22, v104, v105
	v_cvt_pk_bf16_f32 v23, v106, v107
	ds_write2_b64 v8, v[4:5], v[6:7] offset0:64 offset1:68
	v_cvt_pk_bf16_f32 v4, v80, v81
	v_cvt_pk_bf16_f32 v5, v82, v83
	v_cvt_pk_bf16_f32 v6, v64, v65
	v_cvt_pk_bf16_f32 v7, v66, v67
	v_mfma_f32_16x16x32_bf16 v[28:31], v[136:139], v[162:165], v[28:31]
	ds_write2_b64 v40, v[20:21], v[22:23] offset0:32 offset1:36
	v_cvt_pk_bf16_f32 v20, v84, v85
	v_cvt_pk_bf16_f32 v21, v86, v87
	v_cvt_pk_bf16_f32 v22, v68, v69
	v_cvt_pk_bf16_f32 v23, v70, v71
	ds_write2_b64 v8, v[4:5], v[6:7] offset0:72 offset1:76
	v_cvt_pk_bf16_f32 v4, v48, v49
	v_cvt_pk_bf16_f32 v5, v50, v51
	v_cvt_pk_bf16_f32 v6, v32, v33
	v_cvt_pk_bf16_f32 v7, v34, v35
	v_mfma_f32_16x16x32_bf16 v[12:15], v[140:143], v[162:165], v[12:15]
	ds_write2_b64 v40, v[20:21], v[22:23] offset0:40 offset1:44
	ds_write2_b64 v8, v[4:5], v[6:7] offset0:80 offset1:84
	v_cvt_pk_bf16_f32 v4, v16, v17
	v_mfma_f32_16x16x32_bf16 v[20:23], v[144:147], v[162:165], v[88:91]
	v_cvt_pk_bf16_f32 v5, v18, v19
	v_cvt_pk_bf16_f32 v0, v0, v1
	v_cvt_pk_bf16_f32 v1, v2, v3
	ds_write2_b64 v8, v[4:5], v[0:1] offset0:88 offset1:92
	v_cvt_pk_bf16_f32 v0, v112, v113
	v_cvt_pk_bf16_f32 v1, v114, v115
	v_cvt_pk_bf16_f32 v2, v96, v97
	v_cvt_pk_bf16_f32 v3, v98, v99
	v_add_u32_e32 v4, 0x3000, v128
	ds_write2_b64 v4, v[0:1], v[2:3] offset0:96 offset1:100
	v_cvt_pk_bf16_f32 v0, v76, v77
	v_cvt_pk_bf16_f32 v1, v78, v79
	v_cvt_pk_bf16_f32 v2, v60, v61
	v_cvt_pk_bf16_f32 v3, v62, v63
	v_mfma_f32_16x16x32_bf16 v[36:39], v[136:139], v[154:157], v[36:39]
	ds_write2_b64 v4, v[0:1], v[2:3] offset0:104 offset1:108
	v_cvt_pk_bf16_f32 v0, v44, v45
	v_cvt_pk_bf16_f32 v1, v46, v47
	v_cvt_pk_bf16_f32 v2, v28, v29
	v_cvt_pk_bf16_f32 v3, v30, v31
	ds_write2_b64 v4, v[0:1], v[2:3] offset0:112 offset1:116
	v_cvt_pk_bf16_f32 v0, v12, v13
	v_cvt_pk_bf16_f32 v1, v14, v15
	v_cvt_pk_bf16_f32 v2, v20, v21
	v_cvt_pk_bf16_f32 v3, v22, v23
	ds_write2_b64 v4, v[0:1], v[2:3] offset0:120 offset1:124
	v_lshlrev_b32_e32 v0, 3, v148
	v_and_b32_e32 v32, 0x78, v0
	v_cvt_pk_bf16_f32 v26, v36, v37
	v_cvt_pk_bf16_f32 v27, v38, v39
	v_lshl_or_b32 v134, s44, 7, v32
	ds_write2_b64 v40, v[24:25], v[26:27] offset0:48 offset1:52
	v_lshlrev_b64 v[24:25], 2, v[134:135]
	v_lshl_add_u64 v[16:17], s[10:11], 0, v[24:25]
	v_cvt_pk_bf16_f32 v72, v72, v73
	v_cvt_pk_bf16_f32 v73, v74, v75
	v_lshl_add_u64 v[12:13], v[16:17], 0, s[2:3]
	s_movk_i32 s2, 0x2000
	ds_write2_b64 v128, v[124:125], v[108:109] offset1:4
	ds_write2_b64 v128, v[92:93], v[72:73] offset0:8 offset1:12
	v_add_co_u32_e32 v8, vcc, s2, v16
	s_mov_b64 s[2:3], 0x5800
	s_waitcnt lgkmcnt(0)
	s_barrier
	v_addc_co_u32_e32 v9, vcc, 0, v17, vcc
	v_lshl_add_u64 v[20:21], v[16:17], 0, s[2:3]
	s_movk_i32 s2, 0x5000
	v_add_co_u32_e32 v16, vcc, s2, v16
	v_lshl_add_u64 v[28:29], s[12:13], 0, v[24:25]
	s_nop 0
	v_addc_co_u32_e32 v17, vcc, 0, v17, vcc
	s_nop 0
	s_nop 0
	s_nop 0
	s_nop 0
	s_nop 0
	v_ashrrev_i32_e32 v33, 4, v148
	v_mul_lo_u32 v34, v33, s51
	s_mov_b32 s44, 0
	v_lshl_add_u64 v[40:41], v[134:135], 1, s[22:23]
	v_lshl_add_u32 v44, v32, 1, v34
	v_add_u32_e32 v45, 31, v33
	s_waitcnt vmcnt(0)
	s_mov_b32 s32, 1
	s_add_i32 s2, s92, 0xff
	s_ashr_i32 s3, s92, 12
	s_ashr_i32 s2, s2, 12
	s_cmp_eq_u32 s2, s3
	s_cbranch_scc1 .Lup_fast
	s_mov_b32 s32, 3
	s_add_i32 s2, s92, 0xff
	s_cmp_lt_i32 s2, s81
	s_cbranch_scc1 .Lup_fast
	s_mov_b32 s32, 0
	s_branch .LBB0_2308

.LBB0_2355:
	s_waitcnt lgkmcnt(0)
	s_mov_b32 s99, 0x10000
	s_mov_b32 s100, 0x80
	s_mov_b32 s101, 0
	s_add_i32 m0, s12, 0x10000
	s_nop 0
	global_load_lds_dwordx4 v[128:129], off
	v_lshl_add_u64 v[128:129], v[128:129], 0, s[100:101]
	s_add_i32 m0, s12, 0x18000
	s_nop 0
	global_load_lds_dwordx4 v[140:141], off
	v_lshl_add_u64 v[140:141], v[140:141], 0, s[100:101]
	s_add_i32 m0, s13, 0x10000
	s_nop 0
	global_load_lds_dwordx4 v[130:131], off
	v_lshl_add_u64 v[130:131], v[130:131], 0, s[100:101]
	s_add_i32 m0, s13, 0x18000
	s_nop 0
	global_load_lds_dwordx4 v[142:143], off
	v_lshl_add_u64 v[142:143], v[142:143], 0, s[100:101]
	s_add_i32 m0, s29, 0x10000
	s_nop 0
	global_load_lds_dwordx4 v[136:137], off
	v_lshl_add_u64 v[136:137], v[136:137], 0, s[100:101]
	s_add_i32 m0, s29, 0x18000
	s_nop 0
	global_load_lds_dwordx4 v[144:145], off
	v_lshl_add_u64 v[144:145], v[144:145], 0, s[100:101]
	s_add_i32 m0, s31, 0x10000
	s_nop 0
	global_load_lds_dwordx4 v[138:139], off
	v_lshl_add_u64 v[138:139], v[138:139], 0, s[100:101]
	s_add_i32 m0, s31, 0x18000
	s_nop 0
	global_load_lds_dwordx4 v[146:147], off
	v_lshl_add_u64 v[146:147], v[146:147], 0, s[100:101]
	v_add_u32_e32 v164, v151, v149
	v_add_u32_e32 v134, v151, v148
	ds_read_b128 v[152:155], v164 offset:32768
	ds_read_b128 v[156:159], v164 offset:34816
	ds_read_b128 v[160:163], v164 offset:36864
	ds_read_b128 v[164:167], v164 offset:38912
	ds_read_b128 v[168:171], v134 offset:0
	ds_read_b128 v[172:175], v134 offset:2048
	ds_read_b128 v[176:179], v134 offset:4096
	ds_read_b128 v[180:183], v134 offset:6144
	ds_read_b128 v[198:201], v134 offset:8192
	ds_read_b128 v[202:205], v134 offset:10240
	ds_read_b128 v[206:209], v134 offset:12288
	ds_read_b128 v[210:213], v134 offset:14336
	s_waitcnt lgkmcnt(4)
	v_mfma_f32_16x16x32_bf16 v[124:127], v[168:171], v[152:155], 0
	v_mfma_f32_16x16x32_bf16 v[120:123], v[168:171], v[156:159], 0
	v_mfma_f32_16x16x32_bf16 v[116:119], v[168:171], v[160:163], 0
	v_mfma_f32_16x16x32_bf16 v[112:115], v[168:171], v[164:167], 0
	v_mfma_f32_16x16x32_bf16 v[108:111], v[172:175], v[152:155], 0
	v_mfma_f32_16x16x32_bf16 v[104:107], v[172:175], v[156:159], 0
	v_mfma_f32_16x16x32_bf16 v[100:103], v[172:175], v[160:163], 0
	v_mfma_f32_16x16x32_bf16 v[96:99], v[172:175], v[164:167], 0
	v_mfma_f32_16x16x32_bf16 v[92:95], v[176:179], v[152:155], 0
	v_mfma_f32_16x16x32_bf16 v[84:87], v[176:179], v[156:159], 0
	v_mfma_f32_16x16x32_bf16 v[80:83], v[176:179], v[160:163], 0
	v_mfma_f32_16x16x32_bf16 v[76:79], v[176:179], v[164:167], 0
	v_mfma_f32_16x16x32_bf16 v[72:75], v[180:183], v[152:155], 0
	v_mfma_f32_16x16x32_bf16 v[68:71], v[180:183], v[156:159], 0
	v_mfma_f32_16x16x32_bf16 v[64:67], v[180:183], v[160:163], 0
	v_mfma_f32_16x16x32_bf16 v[60:63], v[180:183], v[164:167], 0
	v_add_u32_e32 v180, v150, v149
	v_add_u32_e32 v134, v150, v148
	ds_read_b128 v[168:171], v180 offset:32768
	ds_read_b128 v[172:175], v180 offset:34816
	ds_read_b128 v[176:179], v180 offset:36864
	ds_read_b128 v[180:183], v180 offset:38912
	ds_read_b128 v[214:217], v134 offset:0
	ds_read_b128 v[218:221], v134 offset:2048
	ds_read_b128 v[222:225], v134 offset:4096
	ds_read_b128 v[226:229], v134 offset:6144
	s_waitcnt lgkmcnt(8)
	v_mfma_f32_16x16x32_bf16 v[56:59], v[198:201], v[152:155], 0
	v_mfma_f32_16x16x32_bf16 v[52:55], v[198:201], v[156:159], 0
	v_mfma_f32_16x16x32_bf16 v[48:51], v[198:201], v[160:163], 0
	v_mfma_f32_16x16x32_bf16 v[44:47], v[198:201], v[164:167], 0
	v_mfma_f32_16x16x32_bf16 v[40:43], v[202:205], v[152:155], 0
	v_mfma_f32_16x16x32_bf16 v[36:39], v[202:205], v[156:159], 0
	v_mfma_f32_16x16x32_bf16 v[32:35], v[202:205], v[160:163], 0
	v_mfma_f32_16x16x32_bf16 v[28:31], v[202:205], v[164:167], 0
	v_mfma_f32_16x16x32_bf16 v[24:27], v[206:209], v[152:155], 0
	v_mfma_f32_16x16x32_bf16 v[20:23], v[206:209], v[156:159], 0
	v_mfma_f32_16x16x32_bf16 v[16:19], v[206:209], v[160:163], 0
	v_mfma_f32_16x16x32_bf16 v[12:15], v[206:209], v[164:167], 0
	v_mfma_f32_16x16x32_bf16 v[8:11], v[210:213], v[152:155], 0
	v_mfma_f32_16x16x32_bf16 v[4:7], v[210:213], v[156:159], 0
	v_mfma_f32_16x16x32_bf16 v[0:3], v[210:213], v[160:163], 0
	v_mfma_f32_16x16x32_bf16 v[88:91], v[210:213], v[164:167], 0
	ds_read_b128 v[152:155], v134 offset:8192
	ds_read_b128 v[156:159], v134 offset:10240
	ds_read_b128 v[160:163], v134 offset:12288
	ds_read_b128 v[164:167], v134 offset:14336
	s_waitcnt lgkmcnt(4)
	v_mfma_f32_16x16x32_bf16 v[124:127], v[214:217], v[168:171], v[124:127]
	v_mfma_f32_16x16x32_bf16 v[120:123], v[214:217], v[172:175], v[120:123]
	v_mfma_f32_16x16x32_bf16 v[116:119], v[214:217], v[176:179], v[116:119]
	v_mfma_f32_16x16x32_bf16 v[112:115], v[214:217], v[180:183], v[112:115]
	v_mfma_f32_16x16x32_bf16 v[108:111], v[218:221], v[168:171], v[108:111]
	v_mfma_f32_16x16x32_bf16 v[104:107], v[218:221], v[172:175], v[104:107]
	v_mfma_f32_16x16x32_bf16 v[100:103], v[218:221], v[176:179], v[100:103]
	v_mfma_f32_16x16x32_bf16 v[96:99], v[218:221], v[180:183], v[96:99]
	v_mfma_f32_16x16x32_bf16 v[92:95], v[222:225], v[168:171], v[92:95]
	v_mfma_f32_16x16x32_bf16 v[84:87], v[222:225], v[172:175], v[84:87]
	v_mfma_f32_16x16x32_bf16 v[80:83], v[222:225], v[176:179], v[80:83]
	v_mfma_f32_16x16x32_bf16 v[76:79], v[222:225], v[180:183], v[76:79]
	v_mfma_f32_16x16x32_bf16 v[72:75], v[226:229], v[168:171], v[72:75]
	v_mfma_f32_16x16x32_bf16 v[68:71], v[226:229], v[172:175], v[68:71]
	v_mfma_f32_16x16x32_bf16 v[64:67], v[226:229], v[176:179], v[64:67]
	v_mfma_f32_16x16x32_bf16 v[60:63], v[226:229], v[180:183], v[60:63]
	s_waitcnt lgkmcnt(0)
	v_mfma_f32_16x16x32_bf16 v[56:59], v[152:155], v[168:171], v[56:59]
	v_mfma_f32_16x16x32_bf16 v[52:55], v[152:155], v[172:175], v[52:55]
	v_mfma_f32_16x16x32_bf16 v[48:51], v[152:155], v[176:179], v[48:51]
	v_mfma_f32_16x16x32_bf16 v[44:47], v[152:155], v[180:183], v[44:47]
	s_waitcnt vmcnt(0)
	s_barrier
	v_add3_u32 v210, v151, v149, s99
	v_add3_u32 v134, v151, v148, s99
	v_mfma_f32_16x16x32_bf16 v[40:43], v[156:159], v[168:171], v[40:43]
	ds_read_b128 v[198:201], v210 offset:32768
	ds_read_b128 v[202:205], v210 offset:34816
	v_mfma_f32_16x16x32_bf16 v[36:39], v[156:159], v[172:175], v[36:39]
	ds_read_b128 v[206:209], v210 offset:36864
	ds_read_b128 v[210:213], v210 offset:38912
	v_mfma_f32_16x16x32_bf16 v[32:35], v[156:159], v[176:179], v[32:35]
	ds_read_b128 v[214:217], v134 offset:0
	ds_read_b128 v[218:221], v134 offset:2048
	v_mfma_f32_16x16x32_bf16 v[28:31], v[156:159], v[180:183], v[28:31]
	ds_read_b128 v[222:225], v134 offset:4096
	ds_read_b128 v[226:229], v134 offset:6144
	s_mov_b32 m0, s12
	v_mfma_f32_16x16x32_bf16 v[24:27], v[160:163], v[168:171], v[24:27]
	global_load_lds_dwordx4 v[128:129], off
	v_lshl_add_u64 v[128:129], v[128:129], 0, s[100:101]
	s_add_i32 m0, s12, 0x8000
	v_mfma_f32_16x16x32_bf16 v[20:23], v[160:163], v[172:175], v[20:23]
	global_load_lds_dwordx4 v[140:141], off
	v_lshl_add_u64 v[140:141], v[140:141], 0, s[100:101]
	s_mov_b32 m0, s13
	v_mfma_f32_16x16x32_bf16 v[16:19], v[160:163], v[176:179], v[16:19]
	global_load_lds_dwordx4 v[130:131], off
	v_lshl_add_u64 v[130:131], v[130:131], 0, s[100:101]
	s_add_i32 m0, s13, 0x8000
	v_mfma_f32_16x16x32_bf16 v[12:15], v[160:163], v[180:183], v[12:15]
	global_load_lds_dwordx4 v[142:143], off
	v_lshl_add_u64 v[142:143], v[142:143], 0, s[100:101]
	s_mov_b32 m0, s29
	v_mfma_f32_16x16x32_bf16 v[8:11], v[164:167], v[168:171], v[8:11]
	global_load_lds_dwordx4 v[136:137], off
	v_lshl_add_u64 v[136:137], v[136:137], 0, s[100:101]
	s_add_i32 m0, s29, 0x8000
	v_mfma_f32_16x16x32_bf16 v[4:7], v[164:167], v[172:175], v[4:7]
	global_load_lds_dwordx4 v[144:145], off
	v_lshl_add_u64 v[144:145], v[144:145], 0, s[100:101]
	s_mov_b32 m0, s31
	v_mfma_f32_16x16x32_bf16 v[0:3], v[164:167], v[176:179], v[0:3]
	global_load_lds_dwordx4 v[138:139], off
	v_lshl_add_u64 v[138:139], v[138:139], 0, s[100:101]
	s_add_i32 m0, s31, 0x8000
	v_mfma_f32_16x16x32_bf16 v[88:91], v[164:167], v[180:183], v[88:91]
	global_load_lds_dwordx4 v[146:147], off
	v_lshl_add_u64 v[146:147], v[146:147], 0, s[100:101]
	ds_read_b128 v[152:155], v134 offset:8192
	ds_read_b128 v[156:159], v134 offset:10240
	ds_read_b128 v[160:163], v134 offset:12288
	ds_read_b128 v[164:167], v134 offset:14336
	s_waitcnt lgkmcnt(4)
	v_mfma_f32_16x16x32_bf16 v[124:127], v[214:217], v[198:201], v[124:127]
	v_mfma_f32_16x16x32_bf16 v[120:123], v[214:217], v[202:205], v[120:123]
	v_mfma_f32_16x16x32_bf16 v[116:119], v[214:217], v[206:209], v[116:119]
	v_mfma_f32_16x16x32_bf16 v[112:115], v[214:217], v[210:213], v[112:115]
	v_mfma_f32_16x16x32_bf16 v[108:111], v[218:221], v[198:201], v[108:111]
	v_mfma_f32_16x16x32_bf16 v[104:107], v[218:221], v[202:205], v[104:107]
	v_mfma_f32_16x16x32_bf16 v[100:103], v[218:221], v[206:209], v[100:103]
	v_mfma_f32_16x16x32_bf16 v[96:99], v[218:221], v[210:213], v[96:99]
	v_mfma_f32_16x16x32_bf16 v[92:95], v[222:225], v[198:201], v[92:95]
	v_mfma_f32_16x16x32_bf16 v[84:87], v[222:225], v[202:205], v[84:87]
	v_mfma_f32_16x16x32_bf16 v[80:83], v[222:225], v[206:209], v[80:83]
	v_mfma_f32_16x16x32_bf16 v[76:79], v[222:225], v[210:213], v[76:79]
	v_mfma_f32_16x16x32_bf16 v[72:75], v[226:229], v[198:201], v[72:75]
	v_mfma_f32_16x16x32_bf16 v[68:71], v[226:229], v[202:205], v[68:71]
	v_mfma_f32_16x16x32_bf16 v[64:67], v[226:229], v[206:209], v[64:67]
	v_mfma_f32_16x16x32_bf16 v[60:63], v[226:229], v[210:213], v[60:63]
	v_add3_u32 v226, v150, v149, s99
	v_add3_u32 v134, v150, v148, s99
	ds_read_b128 v[214:217], v226 offset:32768
	ds_read_b128 v[218:221], v226 offset:34816
	ds_read_b128 v[222:225], v226 offset:36864
	ds_read_b128 v[226:229], v226 offset:38912
	ds_read_b128 v[168:171], v134 offset:0
	ds_read_b128 v[172:175], v134 offset:2048
	ds_read_b128 v[176:179], v134 offset:4096
	ds_read_b128 v[180:183], v134 offset:6144
	s_waitcnt lgkmcnt(8)
	v_mfma_f32_16x16x32_bf16 v[56:59], v[152:155], v[198:201], v[56:59]
	v_mfma_f32_16x16x32_bf16 v[52:55], v[152:155], v[202:205], v[52:55]
	v_mfma_f32_16x16x32_bf16 v[48:51], v[152:155], v[206:209], v[48:51]
	v_mfma_f32_16x16x32_bf16 v[44:47], v[152:155], v[210:213], v[44:47]
	v_mfma_f32_16x16x32_bf16 v[40:43], v[156:159], v[198:201], v[40:43]
	v_mfma_f32_16x16x32_bf16 v[36:39], v[156:159], v[202:205], v[36:39]
	v_mfma_f32_16x16x32_bf16 v[32:35], v[156:159], v[206:209], v[32:35]
	v_mfma_f32_16x16x32_bf16 v[28:31], v[156:159], v[210:213], v[28:31]
	v_mfma_f32_16x16x32_bf16 v[24:27], v[160:163], v[198:201], v[24:27]
	v_mfma_f32_16x16x32_bf16 v[20:23], v[160:163], v[202:205], v[20:23]
	v_mfma_f32_16x16x32_bf16 v[16:19], v[160:163], v[206:209], v[16:19]
	v_mfma_f32_16x16x32_bf16 v[12:15], v[160:163], v[210:213], v[12:15]
	v_mfma_f32_16x16x32_bf16 v[8:11], v[164:167], v[198:201], v[8:11]
	v_mfma_f32_16x16x32_bf16 v[4:7], v[164:167], v[202:205], v[4:7]
	v_mfma_f32_16x16x32_bf16 v[0:3], v[164:167], v[206:209], v[0:3]
	v_mfma_f32_16x16x32_bf16 v[88:91], v[164:167], v[210:213], v[88:91]
	ds_read_b128 v[198:201], v134 offset:8192
	ds_read_b128 v[202:205], v134 offset:10240
	ds_read_b128 v[206:209], v134 offset:12288
	ds_read_b128 v[210:213], v134 offset:14336
	s_waitcnt lgkmcnt(4)
	v_mfma_f32_16x16x32_bf16 v[124:127], v[168:171], v[214:217], v[124:127]
	v_mfma_f32_16x16x32_bf16 v[120:123], v[168:171], v[218:221], v[120:123]
	v_mfma_f32_16x16x32_bf16 v[116:119], v[168:171], v[222:225], v[116:119]
	v_mfma_f32_16x16x32_bf16 v[112:115], v[168:171], v[226:229], v[112:115]
	v_mfma_f32_16x16x32_bf16 v[108:111], v[172:175], v[214:217], v[108:111]
	v_mfma_f32_16x16x32_bf16 v[104:107], v[172:175], v[218:221], v[104:107]
	v_mfma_f32_16x16x32_bf16 v[100:103], v[172:175], v[222:225], v[100:103]
	v_mfma_f32_16x16x32_bf16 v[96:99], v[172:175], v[226:229], v[96:99]
	v_mfma_f32_16x16x32_bf16 v[92:95], v[176:179], v[214:217], v[92:95]
	v_mfma_f32_16x16x32_bf16 v[84:87], v[176:179], v[218:221], v[84:87]
	v_mfma_f32_16x16x32_bf16 v[80:83], v[176:179], v[222:225], v[80:83]
	v_mfma_f32_16x16x32_bf16 v[76:79], v[176:179], v[226:229], v[76:79]
	v_mfma_f32_16x16x32_bf16 v[72:75], v[180:183], v[214:217], v[72:75]
	v_mfma_f32_16x16x32_bf16 v[68:71], v[180:183], v[218:221], v[68:71]
	v_mfma_f32_16x16x32_bf16 v[64:67], v[180:183], v[222:225], v[64:67]
	v_mfma_f32_16x16x32_bf16 v[60:63], v[180:183], v[226:229], v[60:63]
	s_waitcnt lgkmcnt(0)
	v_mfma_f32_16x16x32_bf16 v[56:59], v[198:201], v[214:217], v[56:59]
	v_mfma_f32_16x16x32_bf16 v[52:55], v[198:201], v[218:221], v[52:55]
	v_mfma_f32_16x16x32_bf16 v[48:51], v[198:201], v[222:225], v[48:51]
	v_mfma_f32_16x16x32_bf16 v[44:47], v[198:201], v[226:229], v[44:47]
	s_waitcnt vmcnt(0)
	s_barrier
	v_add_u32_e32 v164, v151, v149
	v_add_u32_e32 v134, v151, v148
	v_mfma_f32_16x16x32_bf16 v[40:43], v[202:205], v[214:217], v[40:43]
	ds_read_b128 v[152:155], v164 offset:32768
	ds_read_b128 v[156:159], v164 offset:34816
	v_mfma_f32_16x16x32_bf16 v[36:39], v[202:205], v[218:221], v[36:39]
	ds_read_b128 v[160:163], v164 offset:36864
	ds_read_b128 v[164:167], v164 offset:38912
	v_mfma_f32_16x16x32_bf16 v[32:35], v[202:205], v[222:225], v[32:35]
	ds_read_b128 v[168:171], v134 offset:0
	ds_read_b128 v[172:175], v134 offset:2048
	v_mfma_f32_16x16x32_bf16 v[28:31], v[202:205], v[226:229], v[28:31]
	ds_read_b128 v[176:179], v134 offset:4096
	ds_read_b128 v[180:183], v134 offset:6144
	s_add_i32 m0, s12, 0x10000
	v_mfma_f32_16x16x32_bf16 v[24:27], v[206:209], v[214:217], v[24:27]
	global_load_lds_dwordx4 v[128:129], off
	v_lshl_add_u64 v[128:129], v[128:129], 0, s[100:101]
	s_add_i32 m0, s12, 0x18000
	v_mfma_f32_16x16x32_bf16 v[20:23], v[206:209], v[218:221], v[20:23]
	global_load_lds_dwordx4 v[140:141], off
	v_lshl_add_u64 v[140:141], v[140:141], 0, s[100:101]
	s_add_i32 m0, s13, 0x10000
	v_mfma_f32_16x16x32_bf16 v[16:19], v[206:209], v[222:225], v[16:19]
	global_load_lds_dwordx4 v[130:131], off
	v_lshl_add_u64 v[130:131], v[130:131], 0, s[100:101]
	s_add_i32 m0, s13, 0x18000
	v_mfma_f32_16x16x32_bf16 v[12:15], v[206:209], v[226:229], v[12:15]
	global_load_lds_dwordx4 v[142:143], off
	v_lshl_add_u64 v[142:143], v[142:143], 0, s[100:101]
	s_add_i32 m0, s29, 0x10000
	v_mfma_f32_16x16x32_bf16 v[8:11], v[210:213], v[214:217], v[8:11]
	global_load_lds_dwordx4 v[136:137], off
	v_lshl_add_u64 v[136:137], v[136:137], 0, s[100:101]
	s_add_i32 m0, s29, 0x18000
	v_mfma_f32_16x16x32_bf16 v[4:7], v[210:213], v[218:221], v[4:7]
	global_load_lds_dwordx4 v[144:145], off
	v_lshl_add_u64 v[144:145], v[144:145], 0, s[100:101]
	s_add_i32 m0, s31, 0x10000
	v_mfma_f32_16x16x32_bf16 v[0:3], v[210:213], v[222:225], v[0:3]
	global_load_lds_dwordx4 v[138:139], off
	v_lshl_add_u64 v[138:139], v[138:139], 0, s[100:101]
	s_add_i32 m0, s31, 0x18000
	v_mfma_f32_16x16x32_bf16 v[88:91], v[210:213], v[226:229], v[88:91]
	global_load_lds_dwordx4 v[146:147], off
	v_lshl_add_u64 v[146:147], v[146:147], 0, s[100:101]
	s_movk_i32 s4, 0x100
.Lg_down_loop:
	ds_read_b128 v[198:201], v134 offset:8192
	ds_read_b128 v[202:205], v134 offset:10240
	ds_read_b128 v[206:209], v134 offset:12288
	ds_read_b128 v[210:213], v134 offset:14336
	s_waitcnt lgkmcnt(4)
	v_mfma_f32_16x16x32_bf16 v[124:127], v[168:171], v[152:155], v[124:127]
	v_mfma_f32_16x16x32_bf16 v[120:123], v[168:171], v[156:159], v[120:123]
	v_mfma_f32_16x16x32_bf16 v[116:119], v[168:171], v[160:163], v[116:119]
	v_mfma_f32_16x16x32_bf16 v[112:115], v[168:171], v[164:167], v[112:115]
	v_mfma_f32_16x16x32_bf16 v[108:111], v[172:175], v[152:155], v[108:111]
	v_mfma_f32_16x16x32_bf16 v[104:107], v[172:175], v[156:159], v[104:107]
	v_mfma_f32_16x16x32_bf16 v[100:103], v[172:175], v[160:163], v[100:103]
	v_mfma_f32_16x16x32_bf16 v[96:99], v[172:175], v[164:167], v[96:99]
	v_mfma_f32_16x16x32_bf16 v[92:95], v[176:179], v[152:155], v[92:95]
	v_mfma_f32_16x16x32_bf16 v[84:87], v[176:179], v[156:159], v[84:87]
	v_mfma_f32_16x16x32_bf16 v[80:83], v[176:179], v[160:163], v[80:83]
	v_mfma_f32_16x16x32_bf16 v[76:79], v[176:179], v[164:167], v[76:79]
	v_mfma_f32_16x16x32_bf16 v[72:75], v[180:183], v[152:155], v[72:75]
	v_mfma_f32_16x16x32_bf16 v[68:71], v[180:183], v[156:159], v[68:71]
	v_mfma_f32_16x16x32_bf16 v[64:67], v[180:183], v[160:163], v[64:67]
	v_mfma_f32_16x16x32_bf16 v[60:63], v[180:183], v[164:167], v[60:63]
	v_add_u32_e32 v180, v150, v149
	v_add_u32_e32 v134, v150, v148
	ds_read_b128 v[168:171], v180 offset:32768
	ds_read_b128 v[172:175], v180 offset:34816
	ds_read_b128 v[176:179], v180 offset:36864
	ds_read_b128 v[180:183], v180 offset:38912
	ds_read_b128 v[214:217], v134 offset:0
	ds_read_b128 v[218:221], v134 offset:2048
	ds_read_b128 v[222:225], v134 offset:4096
	ds_read_b128 v[226:229], v134 offset:6144
	s_waitcnt lgkmcnt(8)
	v_mfma_f32_16x16x32_bf16 v[56:59], v[198:201], v[152:155], v[56:59]
	v_mfma_f32_16x16x32_bf16 v[52:55], v[198:201], v[156:159], v[52:55]
	v_mfma_f32_16x16x32_bf16 v[48:51], v[198:201], v[160:163], v[48:51]
	v_mfma_f32_16x16x32_bf16 v[44:47], v[198:201], v[164:167], v[44:47]
	v_mfma_f32_16x16x32_bf16 v[40:43], v[202:205], v[152:155], v[40:43]
	v_mfma_f32_16x16x32_bf16 v[36:39], v[202:205], v[156:159], v[36:39]
	v_mfma_f32_16x16x32_bf16 v[32:35], v[202:205], v[160:163], v[32:35]
	v_mfma_f32_16x16x32_bf16 v[28:31], v[202:205], v[164:167], v[28:31]
	v_mfma_f32_16x16x32_bf16 v[24:27], v[206:209], v[152:155], v[24:27]
	v_mfma_f32_16x16x32_bf16 v[20:23], v[206:209], v[156:159], v[20:23]
	v_mfma_f32_16x16x32_bf16 v[16:19], v[206:209], v[160:163], v[16:19]
	v_mfma_f32_16x16x32_bf16 v[12:15], v[206:209], v[164:167], v[12:15]
	v_mfma_f32_16x16x32_bf16 v[8:11], v[210:213], v[152:155], v[8:11]
	v_mfma_f32_16x16x32_bf16 v[4:7], v[210:213], v[156:159], v[4:7]
	v_mfma_f32_16x16x32_bf16 v[0:3], v[210:213], v[160:163], v[0:3]
	v_mfma_f32_16x16x32_bf16 v[88:91], v[210:213], v[164:167], v[88:91]
	ds_read_b128 v[152:155], v134 offset:8192
	ds_read_b128 v[156:159], v134 offset:10240
	ds_read_b128 v[160:163], v134 offset:12288
	ds_read_b128 v[164:167], v134 offset:14336
	s_waitcnt lgkmcnt(4)
	v_mfma_f32_16x16x32_bf16 v[124:127], v[214:217], v[168:171], v[124:127]
	v_mfma_f32_16x16x32_bf16 v[120:123], v[214:217], v[172:175], v[120:123]
	v_mfma_f32_16x16x32_bf16 v[116:119], v[214:217], v[176:179], v[116:119]
	v_mfma_f32_16x16x32_bf16 v[112:115], v[214:217], v[180:183], v[112:115]
	v_mfma_f32_16x16x32_bf16 v[108:111], v[218:221], v[168:171], v[108:111]
	v_mfma_f32_16x16x32_bf16 v[104:107], v[218:221], v[172:175], v[104:107]
	v_mfma_f32_16x16x32_bf16 v[100:103], v[218:221], v[176:179], v[100:103]
	v_mfma_f32_16x16x32_bf16 v[96:99], v[218:221], v[180:183], v[96:99]
	v_mfma_f32_16x16x32_bf16 v[92:95], v[222:225], v[168:171], v[92:95]
	v_mfma_f32_16x16x32_bf16 v[84:87], v[222:225], v[172:175], v[84:87]
	v_mfma_f32_16x16x32_bf16 v[80:83], v[222:225], v[176:179], v[80:83]
	v_mfma_f32_16x16x32_bf16 v[76:79], v[222:225], v[180:183], v[76:79]
	v_mfma_f32_16x16x32_bf16 v[72:75], v[226:229], v[168:171], v[72:75]
	v_mfma_f32_16x16x32_bf16 v[68:71], v[226:229], v[172:175], v[68:71]
	v_mfma_f32_16x16x32_bf16 v[64:67], v[226:229], v[176:179], v[64:67]
	v_mfma_f32_16x16x32_bf16 v[60:63], v[226:229], v[180:183], v[60:63]
	s_waitcnt lgkmcnt(0)
	v_mfma_f32_16x16x32_bf16 v[56:59], v[152:155], v[168:171], v[56:59]
	v_mfma_f32_16x16x32_bf16 v[52:55], v[152:155], v[172:175], v[52:55]
	v_mfma_f32_16x16x32_bf16 v[48:51], v[152:155], v[176:179], v[48:51]
	v_mfma_f32_16x16x32_bf16 v[44:47], v[152:155], v[180:183], v[44:47]
	s_waitcnt vmcnt(0)
	s_barrier
	v_add3_u32 v210, v151, v149, s99
	v_add3_u32 v134, v151, v148, s99
	v_mfma_f32_16x16x32_bf16 v[40:43], v[156:159], v[168:171], v[40:43]
	ds_read_b128 v[198:201], v210 offset:32768
	ds_read_b128 v[202:205], v210 offset:34816
	v_mfma_f32_16x16x32_bf16 v[36:39], v[156:159], v[172:175], v[36:39]
	ds_read_b128 v[206:209], v210 offset:36864
	ds_read_b128 v[210:213], v210 offset:38912
	v_mfma_f32_16x16x32_bf16 v[32:35], v[156:159], v[176:179], v[32:35]
	ds_read_b128 v[214:217], v134 offset:0
	ds_read_b128 v[218:221], v134 offset:2048
	v_mfma_f32_16x16x32_bf16 v[28:31], v[156:159], v[180:183], v[28:31]
	ds_read_b128 v[222:225], v134 offset:4096
	ds_read_b128 v[226:229], v134 offset:6144
	s_mov_b32 m0, s12
	v_mfma_f32_16x16x32_bf16 v[24:27], v[160:163], v[168:171], v[24:27]
	global_load_lds_dwordx4 v[128:129], off
	v_lshl_add_u64 v[128:129], v[128:129], 0, s[100:101]
	s_add_i32 m0, s12, 0x8000
	v_mfma_f32_16x16x32_bf16 v[20:23], v[160:163], v[172:175], v[20:23]
	global_load_lds_dwordx4 v[140:141], off
	v_lshl_add_u64 v[140:141], v[140:141], 0, s[100:101]
	s_mov_b32 m0, s13
	v_mfma_f32_16x16x32_bf16 v[16:19], v[160:163], v[176:179], v[16:19]
	global_load_lds_dwordx4 v[130:131], off
	v_lshl_add_u64 v[130:131], v[130:131], 0, s[100:101]
	s_add_i32 m0, s13, 0x8000
	v_mfma_f32_16x16x32_bf16 v[12:15], v[160:163], v[180:183], v[12:15]
	global_load_lds_dwordx4 v[142:143], off
	v_lshl_add_u64 v[142:143], v[142:143], 0, s[100:101]
	s_mov_b32 m0, s29
	v_mfma_f32_16x16x32_bf16 v[8:11], v[164:167], v[168:171], v[8:11]
	global_load_lds_dwordx4 v[136:137], off
	v_lshl_add_u64 v[136:137], v[136:137], 0, s[100:101]
	s_add_i32 m0, s29, 0x8000
	v_mfma_f32_16x16x32_bf16 v[4:7], v[164:167], v[172:175], v[4:7]
	global_load_lds_dwordx4 v[144:145], off
	v_lshl_add_u64 v[144:145], v[144:145], 0, s[100:101]
	s_mov_b32 m0, s31
	v_mfma_f32_16x16x32_bf16 v[0:3], v[164:167], v[176:179], v[0:3]
	global_load_lds_dwordx4 v[138:139], off
	v_lshl_add_u64 v[138:139], v[138:139], 0, s[100:101]
	s_add_i32 m0, s31, 0x8000
	v_mfma_f32_16x16x32_bf16 v[88:91], v[164:167], v[180:183], v[88:91]
	global_load_lds_dwordx4 v[146:147], off
	v_lshl_add_u64 v[146:147], v[146:147], 0, s[100:101]
	ds_read_b128 v[152:155], v134 offset:8192
	ds_read_b128 v[156:159], v134 offset:10240
	ds_read_b128 v[160:163], v134 offset:12288
	ds_read_b128 v[164:167], v134 offset:14336
	s_waitcnt lgkmcnt(4)
	v_mfma_f32_16x16x32_bf16 v[124:127], v[214:217], v[198:201], v[124:127]
	v_mfma_f32_16x16x32_bf16 v[120:123], v[214:217], v[202:205], v[120:123]
	v_mfma_f32_16x16x32_bf16 v[116:119], v[214:217], v[206:209], v[116:119]
	v_mfma_f32_16x16x32_bf16 v[112:115], v[214:217], v[210:213], v[112:115]
	v_mfma_f32_16x16x32_bf16 v[108:111], v[218:221], v[198:201], v[108:111]
	v_mfma_f32_16x16x32_bf16 v[104:107], v[218:221], v[202:205], v[104:107]
	v_mfma_f32_16x16x32_bf16 v[100:103], v[218:221], v[206:209], v[100:103]
	v_mfma_f32_16x16x32_bf16 v[96:99], v[218:221], v[210:213], v[96:99]
	v_mfma_f32_16x16x32_bf16 v[92:95], v[222:225], v[198:201], v[92:95]
	v_mfma_f32_16x16x32_bf16 v[84:87], v[222:225], v[202:205], v[84:87]
	v_mfma_f32_16x16x32_bf16 v[80:83], v[222:225], v[206:209], v[80:83]
	v_mfma_f32_16x16x32_bf16 v[76:79], v[222:225], v[210:213], v[76:79]
	v_mfma_f32_16x16x32_bf16 v[72:75], v[226:229], v[198:201], v[72:75]
	v_mfma_f32_16x16x32_bf16 v[68:71], v[226:229], v[202:205], v[68:71]
	v_mfma_f32_16x16x32_bf16 v[64:67], v[226:229], v[206:209], v[64:67]
	v_mfma_f32_16x16x32_bf16 v[60:63], v[226:229], v[210:213], v[60:63]
	v_add3_u32 v226, v150, v149, s99
	v_add3_u32 v134, v150, v148, s99
	ds_read_b128 v[214:217], v226 offset:32768
	ds_read_b128 v[218:221], v226 offset:34816
	ds_read_b128 v[222:225], v226 offset:36864
	ds_read_b128 v[226:229], v226 offset:38912
	ds_read_b128 v[168:171], v134 offset:0
	ds_read_b128 v[172:175], v134 offset:2048
	ds_read_b128 v[176:179], v134 offset:4096
	ds_read_b128 v[180:183], v134 offset:6144
	s_waitcnt lgkmcnt(8)
	v_mfma_f32_16x16x32_bf16 v[56:59], v[152:155], v[198:201], v[56:59]
	v_mfma_f32_16x16x32_bf16 v[52:55], v[152:155], v[202:205], v[52:55]
	v_mfma_f32_16x16x32_bf16 v[48:51], v[152:155], v[206:209], v[48:51]
	v_mfma_f32_16x16x32_bf16 v[44:47], v[152:155], v[210:213], v[44:47]
	v_mfma_f32_16x16x32_bf16 v[40:43], v[156:159], v[198:201], v[40:43]
	v_mfma_f32_16x16x32_bf16 v[36:39], v[156:159], v[202:205], v[36:39]
	v_mfma_f32_16x16x32_bf16 v[32:35], v[156:159], v[206:209], v[32:35]
	v_mfma_f32_16x16x32_bf16 v[28:31], v[156:159], v[210:213], v[28:31]
	v_mfma_f32_16x16x32_bf16 v[24:27], v[160:163], v[198:201], v[24:27]
	v_mfma_f32_16x16x32_bf16 v[20:23], v[160:163], v[202:205], v[20:23]
	v_mfma_f32_16x16x32_bf16 v[16:19], v[160:163], v[206:209], v[16:19]
	v_mfma_f32_16x16x32_bf16 v[12:15], v[160:163], v[210:213], v[12:15]
	v_mfma_f32_16x16x32_bf16 v[8:11], v[164:167], v[198:201], v[8:11]
	v_mfma_f32_16x16x32_bf16 v[4:7], v[164:167], v[202:205], v[4:7]
	v_mfma_f32_16x16x32_bf16 v[0:3], v[164:167], v[206:209], v[0:3]
	v_mfma_f32_16x16x32_bf16 v[88:91], v[164:167], v[210:213], v[88:91]
	ds_read_b128 v[198:201], v134 offset:8192
	ds_read_b128 v[202:205], v134 offset:10240
	ds_read_b128 v[206:209], v134 offset:12288
	ds_read_b128 v[210:213], v134 offset:14336
	s_waitcnt lgkmcnt(4)
	v_mfma_f32_16x16x32_bf16 v[124:127], v[168:171], v[214:217], v[124:127]
	v_mfma_f32_16x16x32_bf16 v[120:123], v[168:171], v[218:221], v[120:123]
	v_mfma_f32_16x16x32_bf16 v[116:119], v[168:171], v[222:225], v[116:119]
	v_mfma_f32_16x16x32_bf16 v[112:115], v[168:171], v[226:229], v[112:115]
	v_mfma_f32_16x16x32_bf16 v[108:111], v[172:175], v[214:217], v[108:111]
	v_mfma_f32_16x16x32_bf16 v[104:107], v[172:175], v[218:221], v[104:107]
	v_mfma_f32_16x16x32_bf16 v[100:103], v[172:175], v[222:225], v[100:103]
	v_mfma_f32_16x16x32_bf16 v[96:99], v[172:175], v[226:229], v[96:99]
	v_mfma_f32_16x16x32_bf16 v[92:95], v[176:179], v[214:217], v[92:95]
	v_mfma_f32_16x16x32_bf16 v[84:87], v[176:179], v[218:221], v[84:87]
	v_mfma_f32_16x16x32_bf16 v[80:83], v[176:179], v[222:225], v[80:83]
	v_mfma_f32_16x16x32_bf16 v[76:79], v[176:179], v[226:229], v[76:79]
	v_mfma_f32_16x16x32_bf16 v[72:75], v[180:183], v[214:217], v[72:75]
	v_mfma_f32_16x16x32_bf16 v[68:71], v[180:183], v[218:221], v[68:71]
	v_mfma_f32_16x16x32_bf16 v[64:67], v[180:183], v[222:225], v[64:67]
	v_mfma_f32_16x16x32_bf16 v[60:63], v[180:183], v[226:229], v[60:63]
	s_waitcnt lgkmcnt(0)
	v_mfma_f32_16x16x32_bf16 v[56:59], v[198:201], v[214:217], v[56:59]
	v_mfma_f32_16x16x32_bf16 v[52:55], v[198:201], v[218:221], v[52:55]
	v_mfma_f32_16x16x32_bf16 v[48:51], v[198:201], v[222:225], v[48:51]
	v_mfma_f32_16x16x32_bf16 v[44:47], v[198:201], v[226:229], v[44:47]
	s_waitcnt vmcnt(0)
	s_barrier
	v_add_u32_e32 v164, v151, v149
	v_add_u32_e32 v134, v151, v148
	v_mfma_f32_16x16x32_bf16 v[40:43], v[202:205], v[214:217], v[40:43]
	ds_read_b128 v[152:155], v164 offset:32768
	ds_read_b128 v[156:159], v164 offset:34816
	v_mfma_f32_16x16x32_bf16 v[36:39], v[202:205], v[218:221], v[36:39]
	ds_read_b128 v[160:163], v164 offset:36864
	ds_read_b128 v[164:167], v164 offset:38912
	v_mfma_f32_16x16x32_bf16 v[32:35], v[202:205], v[222:225], v[32:35]
	ds_read_b128 v[168:171], v134 offset:0
	ds_read_b128 v[172:175], v134 offset:2048
	v_mfma_f32_16x16x32_bf16 v[28:31], v[202:205], v[226:229], v[28:31]
	ds_read_b128 v[176:179], v134 offset:4096
	ds_read_b128 v[180:183], v134 offset:6144
	s_add_i32 m0, s12, 0x10000
	v_mfma_f32_16x16x32_bf16 v[24:27], v[206:209], v[214:217], v[24:27]
	global_load_lds_dwordx4 v[128:129], off
	v_lshl_add_u64 v[128:129], v[128:129], 0, s[100:101]
	s_add_i32 m0, s12, 0x18000
	v_mfma_f32_16x16x32_bf16 v[20:23], v[206:209], v[218:221], v[20:23]
	global_load_lds_dwordx4 v[140:141], off
	v_lshl_add_u64 v[140:141], v[140:141], 0, s[100:101]
	s_add_i32 m0, s13, 0x10000
	v_mfma_f32_16x16x32_bf16 v[16:19], v[206:209], v[222:225], v[16:19]
	global_load_lds_dwordx4 v[130:131], off
	v_lshl_add_u64 v[130:131], v[130:131], 0, s[100:101]
	s_add_i32 m0, s13, 0x18000
	v_mfma_f32_16x16x32_bf16 v[12:15], v[206:209], v[226:229], v[12:15]
	global_load_lds_dwordx4 v[142:143], off
	v_lshl_add_u64 v[142:143], v[142:143], 0, s[100:101]
	s_add_i32 m0, s29, 0x10000
	v_mfma_f32_16x16x32_bf16 v[8:11], v[210:213], v[214:217], v[8:11]
	global_load_lds_dwordx4 v[136:137], off
	v_lshl_add_u64 v[136:137], v[136:137], 0, s[100:101]
	s_add_i32 m0, s29, 0x18000
	v_mfma_f32_16x16x32_bf16 v[4:7], v[210:213], v[218:221], v[4:7]
	global_load_lds_dwordx4 v[144:145], off
	v_lshl_add_u64 v[144:145], v[144:145], 0, s[100:101]
	s_add_i32 m0, s31, 0x10000
	v_mfma_f32_16x16x32_bf16 v[0:3], v[210:213], v[222:225], v[0:3]
	global_load_lds_dwordx4 v[138:139], off
	v_lshl_add_u64 v[138:139], v[138:139], 0, s[100:101]
	s_add_i32 m0, s31, 0x18000
	v_mfma_f32_16x16x32_bf16 v[88:91], v[210:213], v[226:229], v[88:91]
	global_load_lds_dwordx4 v[146:147], off
	v_lshl_add_u64 v[146:147], v[146:147], 0, s[100:101]
	s_add_u32 s4, s4, 0x100
	s_cmpk_lg_i32 s4, 0x1500
	s_cbranch_scc1 .Lg_down_loop
	ds_read_b128 v[198:201], v134 offset:8192
	ds_read_b128 v[202:205], v134 offset:10240
	ds_read_b128 v[206:209], v134 offset:12288
	ds_read_b128 v[210:213], v134 offset:14336
	s_waitcnt lgkmcnt(4)
	v_mfma_f32_16x16x32_bf16 v[124:127], v[168:171], v[152:155], v[124:127]
	v_mfma_f32_16x16x32_bf16 v[120:123], v[168:171], v[156:159], v[120:123]
	v_mfma_f32_16x16x32_bf16 v[116:119], v[168:171], v[160:163], v[116:119]
	v_mfma_f32_16x16x32_bf16 v[112:115], v[168:171], v[164:167], v[112:115]
	v_mfma_f32_16x16x32_bf16 v[108:111], v[172:175], v[152:155], v[108:111]
	v_mfma_f32_16x16x32_bf16 v[104:107], v[172:175], v[156:159], v[104:107]
	v_mfma_f32_16x16x32_bf16 v[100:103], v[172:175], v[160:163], v[100:103]
	v_mfma_f32_16x16x32_bf16 v[96:99], v[172:175], v[164:167], v[96:99]
	v_mfma_f32_16x16x32_bf16 v[92:95], v[176:179], v[152:155], v[92:95]
	v_mfma_f32_16x16x32_bf16 v[84:87], v[176:179], v[156:159], v[84:87]
	v_mfma_f32_16x16x32_bf16 v[80:83], v[176:179], v[160:163], v[80:83]
	v_mfma_f32_16x16x32_bf16 v[76:79], v[176:179], v[164:167], v[76:79]
	v_mfma_f32_16x16x32_bf16 v[72:75], v[180:183], v[152:155], v[72:75]
	v_mfma_f32_16x16x32_bf16 v[68:71], v[180:183], v[156:159], v[68:71]
	v_mfma_f32_16x16x32_bf16 v[64:67], v[180:183], v[160:163], v[64:67]
	v_mfma_f32_16x16x32_bf16 v[60:63], v[180:183], v[164:167], v[60:63]
	v_add_u32_e32 v180, v150, v149
	v_add_u32_e32 v134, v150, v148
	ds_read_b128 v[168:171], v180 offset:32768
	ds_read_b128 v[172:175], v180 offset:34816
	ds_read_b128 v[176:179], v180 offset:36864
	ds_read_b128 v[180:183], v180 offset:38912
	ds_read_b128 v[214:217], v134 offset:0
	ds_read_b128 v[218:221], v134 offset:2048
	ds_read_b128 v[222:225], v134 offset:4096
	ds_read_b128 v[226:229], v134 offset:6144
	s_waitcnt lgkmcnt(8)
	v_mfma_f32_16x16x32_bf16 v[56:59], v[198:201], v[152:155], v[56:59]
	v_mfma_f32_16x16x32_bf16 v[52:55], v[198:201], v[156:159], v[52:55]
	v_mfma_f32_16x16x32_bf16 v[48:51], v[198:201], v[160:163], v[48:51]
	v_mfma_f32_16x16x32_bf16 v[44:47], v[198:201], v[164:167], v[44:47]
	v_mfma_f32_16x16x32_bf16 v[40:43], v[202:205], v[152:155], v[40:43]
	v_mfma_f32_16x16x32_bf16 v[36:39], v[202:205], v[156:159], v[36:39]
	v_mfma_f32_16x16x32_bf16 v[32:35], v[202:205], v[160:163], v[32:35]
	v_mfma_f32_16x16x32_bf16 v[28:31], v[202:205], v[164:167], v[28:31]
	v_mfma_f32_16x16x32_bf16 v[24:27], v[206:209], v[152:155], v[24:27]
	v_mfma_f32_16x16x32_bf16 v[20:23], v[206:209], v[156:159], v[20:23]
	v_mfma_f32_16x16x32_bf16 v[16:19], v[206:209], v[160:163], v[16:19]
	v_mfma_f32_16x16x32_bf16 v[12:15], v[206:209], v[164:167], v[12:15]
	v_mfma_f32_16x16x32_bf16 v[8:11], v[210:213], v[152:155], v[8:11]
	v_mfma_f32_16x16x32_bf16 v[4:7], v[210:213], v[156:159], v[4:7]
	v_mfma_f32_16x16x32_bf16 v[0:3], v[210:213], v[160:163], v[0:3]
	v_mfma_f32_16x16x32_bf16 v[88:91], v[210:213], v[164:167], v[88:91]
	ds_read_b128 v[152:155], v134 offset:8192
	ds_read_b128 v[156:159], v134 offset:10240
	ds_read_b128 v[160:163], v134 offset:12288
	ds_read_b128 v[164:167], v134 offset:14336
	s_waitcnt lgkmcnt(4)
	v_mfma_f32_16x16x32_bf16 v[124:127], v[214:217], v[168:171], v[124:127]
	v_mfma_f32_16x16x32_bf16 v[120:123], v[214:217], v[172:175], v[120:123]
	v_mfma_f32_16x16x32_bf16 v[116:119], v[214:217], v[176:179], v[116:119]
	v_mfma_f32_16x16x32_bf16 v[112:115], v[214:217], v[180:183], v[112:115]
	v_mfma_f32_16x16x32_bf16 v[108:111], v[218:221], v[168:171], v[108:111]
	v_mfma_f32_16x16x32_bf16 v[104:107], v[218:221], v[172:175], v[104:107]
	v_mfma_f32_16x16x32_bf16 v[100:103], v[218:221], v[176:179], v[100:103]
	v_mfma_f32_16x16x32_bf16 v[96:99], v[218:221], v[180:183], v[96:99]
	v_mfma_f32_16x16x32_bf16 v[92:95], v[222:225], v[168:171], v[92:95]
	v_mfma_f32_16x16x32_bf16 v[84:87], v[222:225], v[172:175], v[84:87]
	v_mfma_f32_16x16x32_bf16 v[80:83], v[222:225], v[176:179], v[80:83]
	v_mfma_f32_16x16x32_bf16 v[76:79], v[222:225], v[180:183], v[76:79]
	v_mfma_f32_16x16x32_bf16 v[72:75], v[226:229], v[168:171], v[72:75]
	v_mfma_f32_16x16x32_bf16 v[68:71], v[226:229], v[172:175], v[68:71]
	v_mfma_f32_16x16x32_bf16 v[64:67], v[226:229], v[176:179], v[64:67]
	v_mfma_f32_16x16x32_bf16 v[60:63], v[226:229], v[180:183], v[60:63]
	s_waitcnt lgkmcnt(0)
	v_mfma_f32_16x16x32_bf16 v[56:59], v[152:155], v[168:171], v[56:59]
	v_mfma_f32_16x16x32_bf16 v[52:55], v[152:155], v[172:175], v[52:55]
	v_mfma_f32_16x16x32_bf16 v[48:51], v[152:155], v[176:179], v[48:51]
	v_mfma_f32_16x16x32_bf16 v[44:47], v[152:155], v[180:183], v[44:47]
	s_waitcnt vmcnt(0)
	s_barrier
	v_mfma_f32_16x16x32_bf16 v[40:43], v[156:159], v[168:171], v[40:43]
	v_mfma_f32_16x16x32_bf16 v[36:39], v[156:159], v[172:175], v[36:39]
	v_mfma_f32_16x16x32_bf16 v[32:35], v[156:159], v[176:179], v[32:35]
	v_mfma_f32_16x16x32_bf16 v[28:31], v[156:159], v[180:183], v[28:31]
	v_mfma_f32_16x16x32_bf16 v[24:27], v[160:163], v[168:171], v[24:27]
	v_mfma_f32_16x16x32_bf16 v[20:23], v[160:163], v[172:175], v[20:23]
	v_mfma_f32_16x16x32_bf16 v[16:19], v[160:163], v[176:179], v[16:19]
	v_mfma_f32_16x16x32_bf16 v[12:15], v[160:163], v[180:183], v[12:15]
	v_mfma_f32_16x16x32_bf16 v[8:11], v[164:167], v[168:171], v[8:11]
	v_mfma_f32_16x16x32_bf16 v[4:7], v[164:167], v[172:175], v[4:7]
	v_mfma_f32_16x16x32_bf16 v[0:3], v[164:167], v[176:179], v[0:3]
	v_mfma_f32_16x16x32_bf16 v[88:91], v[164:167], v[180:183], v[88:91]
	s_movk_i32 s4, 0x1580
	s_mov_b32 s86, 0x10000
	s_mov_b32 s87, 0x2b0000
	s_mov_b32 s44, 0x2b0000
	v_add_u32_e32 v134, s86, v151
	v_add_u32_e32 v144, v134, v149
	v_add_u32_e32 v134, v134, v148
	ds_read_b128 v[128:131], v144 offset:32768
	ds_read_b128 v[136:139], v144 offset:34816
	ds_read_b128 v[140:143], v144 offset:36864
	ds_read_b128 v[144:147], v144 offset:38912
	ds_read_b128 v[152:155], v134
	ds_read_b128 v[156:159], v134 offset:2048
	ds_read_b128 v[160:163], v134 offset:4096
	ds_read_b128 v[164:167], v134 offset:6144
	ds_read_b128 v[168:171], v134 offset:8192
	ds_read_b128 v[172:175], v134 offset:10240
	ds_read_b128 v[176:179], v134 offset:12288
	ds_read_b128 v[180:183], v134 offset:14336
	s_waitcnt lgkmcnt(0)
	v_mfma_f32_16x16x32_bf16 v[124:127], v[152:155], v[128:131], v[124:127]
	v_mfma_f32_16x16x32_bf16 v[120:123], v[152:155], v[136:139], v[120:123]
	v_mfma_f32_16x16x32_bf16 v[116:119], v[152:155], v[140:143], v[116:119]
	v_mfma_f32_16x16x32_bf16 v[112:115], v[152:155], v[144:147], v[112:115]
	v_mfma_f32_16x16x32_bf16 v[108:111], v[156:159], v[128:131], v[108:111]
	v_mfma_f32_16x16x32_bf16 v[104:107], v[156:159], v[136:139], v[104:107]
	v_mfma_f32_16x16x32_bf16 v[100:103], v[156:159], v[140:143], v[100:103]
	v_mfma_f32_16x16x32_bf16 v[96:99], v[156:159], v[144:147], v[96:99]
	v_mfma_f32_16x16x32_bf16 v[84:87], v[160:163], v[136:139], v[84:87]
	v_mfma_f32_16x16x32_bf16 v[76:79], v[160:163], v[144:147], v[76:79]
	v_mfma_f32_16x16x32_bf16 v[72:75], v[164:167], v[128:131], v[72:75]
	v_mfma_f32_16x16x32_bf16 v[68:71], v[164:167], v[136:139], v[68:71]
	v_mfma_f32_16x16x32_bf16 v[64:67], v[164:167], v[140:143], v[64:67]
	v_mfma_f32_16x16x32_bf16 v[152:155], v[160:163], v[128:131], v[92:95]
	v_mfma_f32_16x16x32_bf16 v[156:159], v[160:163], v[140:143], v[80:83]
	v_mfma_f32_16x16x32_bf16 v[160:163], v[164:167], v[144:147], v[60:63]
	s_nop 2
	v_add_u32_e32 v60, s86, v150
	v_add_u32_e32 v61, v60, v149
	v_add_u32_e32 v60, v60, v148
	ds_read_b128 v[164:167], v61 offset:32768
	ds_read_b128 v[198:201], v61 offset:34816
	ds_read_b128 v[202:205], v61 offset:36864
	ds_read_b128 v[206:209], v61 offset:38912
	ds_read_b128 v[80:83], v60
	ds_read_b128 v[148:151], v60 offset:2048
	ds_read_b128 v[210:213], v60 offset:4096
	ds_read_b128 v[214:217], v60 offset:6144
	v_mfma_f32_16x16x32_bf16 v[56:59], v[168:171], v[128:131], v[56:59]
	v_mfma_f32_16x16x32_bf16 v[218:221], v[168:171], v[136:139], v[52:55]
	v_mfma_f32_16x16x32_bf16 v[222:225], v[168:171], v[140:143], v[48:51]
	v_mfma_f32_16x16x32_bf16 v[44:47], v[168:171], v[144:147], v[44:47]
	v_mfma_f32_16x16x32_bf16 v[168:171], v[172:175], v[128:131], v[40:43]
	v_mfma_f32_16x16x32_bf16 v[226:229], v[172:175], v[136:139], v[36:39]
	v_mfma_f32_16x16x32_bf16 v[32:35], v[172:175], v[140:143], v[32:35]
	v_mfma_f32_16x16x32_bf16 v[28:31], v[172:175], v[144:147], v[28:31]
	v_mfma_f32_16x16x32_bf16 v[172:175], v[176:179], v[128:131], v[24:27]
	v_mfma_f32_16x16x32_bf16 v[16:19], v[176:179], v[140:143], v[16:19]
	v_mfma_f32_16x16x32_bf16 v[128:131], v[180:183], v[128:131], v[8:11]
	v_mfma_f32_16x16x32_bf16 v[230:233], v[176:179], v[136:139], v[20:23]
	v_mfma_f32_16x16x32_bf16 v[176:179], v[176:179], v[144:147], v[12:15]
	v_mfma_f32_16x16x32_bf16 v[234:237], v[180:183], v[136:139], v[4:7]
	v_mfma_f32_16x16x32_bf16 v[140:143], v[180:183], v[140:143], v[0:3]
	v_mfma_f32_16x16x32_bf16 v[144:147], v[180:183], v[144:147], v[88:91]
	s_nop 1
	ds_read_b128 v[0:3], v60 offset:8192
	ds_read_b128 v[136:139], v60 offset:10240
	ds_read_b128 v[180:183], v60 offset:12288
	ds_read_b128 v[238:241], v60 offset:14336
	s_waitcnt lgkmcnt(0)
	v_mfma_f32_16x16x32_bf16 v[124:127], v[80:83], v[164:167], v[124:127]
	v_mfma_f32_16x16x32_bf16 v[92:95], v[80:83], v[198:201], v[120:123]
	v_mfma_f32_16x16x32_bf16 v[60:63], v[80:83], v[202:205], v[116:119]
	v_mfma_f32_16x16x32_bf16 v[24:27], v[80:83], v[206:209], v[112:115]
	v_mfma_f32_16x16x32_bf16 v[120:123], v[148:151], v[164:167], v[108:111]
	v_mfma_f32_16x16x32_bf16 v[88:91], v[148:151], v[198:201], v[104:107]
	v_mfma_f32_16x16x32_bf16 v[52:55], v[148:151], v[202:205], v[100:103]
	v_mfma_f32_16x16x32_bf16 v[20:23], v[148:151], v[206:209], v[96:99]
	v_mfma_f32_16x16x32_bf16 v[116:119], v[210:213], v[164:167], v[152:155]
	v_mfma_f32_16x16x32_bf16 v[80:83], v[210:213], v[198:201], v[84:87]
	v_mfma_f32_16x16x32_bf16 v[48:51], v[210:213], v[202:205], v[156:159]
	v_mfma_f32_16x16x32_bf16 v[12:15], v[210:213], v[206:209], v[76:79]
	v_mfma_f32_16x16x32_bf16 v[108:111], v[214:217], v[164:167], v[72:75]
	v_mfma_f32_16x16x32_bf16 v[76:79], v[214:217], v[198:201], v[68:71]
	v_mfma_f32_16x16x32_bf16 v[40:43], v[214:217], v[202:205], v[64:67]
	v_mfma_f32_16x16x32_bf16 v[8:11], v[214:217], v[206:209], v[160:163]
	v_mfma_f32_16x16x32_bf16 v[104:107], v[0:3], v[164:167], v[56:59]
	s_waitcnt vmcnt(0)
	s_waitcnt lgkmcnt(0)
	s_barrier
	v_mfma_f32_16x16x32_bf16 v[68:71], v[0:3], v[198:201], v[218:221]
	v_cvt_pk_bf16_f32 v134, v124, v125
	v_mfma_f32_16x16x32_bf16 v[36:39], v[0:3], v[202:205], v[222:225]
	v_mfma_f32_16x16x32_bf16 v[4:7], v[0:3], v[206:209], v[44:47]
	v_mfma_f32_16x16x32_bf16 v[100:103], v[136:139], v[164:167], v[168:171]
	v_mfma_f32_16x16x32_bf16 v[64:67], v[136:139], v[198:201], v[226:229]
	v_mfma_f32_16x16x32_bf16 v[32:35], v[136:139], v[202:205], v[32:35]
	v_mfma_f32_16x16x32_bf16 v[0:3], v[136:139], v[206:209], v[28:31]
	v_mov_b32_e32 v137, v184
	v_cvt_pk_bf16_f32 v136, v126, v127
	v_mfma_f32_16x16x32_bf16 v[96:99], v[180:183], v[164:167], v[172:175]
	v_and_b32_e32 v28, 16, v137
	v_cmp_eq_u32_e64 s[4:5], 0, v28
	v_cmp_ne_u32_e32 vcc, 0, v28
	v_mfma_f32_16x16x32_bf16 v[72:75], v[180:183], v[198:201], v[230:233]
	v_cvt_pk_bf16_f32 v138, v120, v121
	v_cvt_pk_bf16_f32 v139, v122, v123
	v_mfma_f32_16x16x32_bf16 v[44:47], v[180:183], v[202:205], v[16:19]
	v_mfma_f32_16x16x32_bf16 v[16:19], v[180:183], v[206:209], v[176:179]
	v_mfma_f32_16x16x32_bf16 v[112:115], v[238:241], v[164:167], v[128:131]
	v_mfma_f32_16x16x32_bf16 v[84:87], v[238:241], v[198:201], v[234:237]
	s_nop 1
	v_mov_b32_e32 v128, v134
	v_mov_b32_e32 v130, v138
	v_mov_b32_e32 v131, v139
	v_mfma_f32_16x16x32_bf16 v[56:59], v[238:241], v[202:205], v[140:143]
	v_mov_b32_e32 v129, v136
	v_permlane16_swap_b32_e32 v128, v130
	v_mfma_f32_16x16x32_bf16 v[28:31], v[238:241], v[206:209], v[144:147]
	v_permlane16_swap_b32_e32 v129, v131
	s_and_saveexec_b64 s[12:13], vcc
	s_xor_b64 s[12:13], exec, s[12:13]
	v_mov_b32_e32 v131, v139
	v_mov_b32_e32 v130, v138
	s_andn2_saveexec_b64 s[12:13], s[12:13]
	v_mov_b32_e32 v128, v134
	v_mov_b32_e32 v129, v136
	s_or_b64 exec, exec, s[12:13]
	v_ashrrev_i32_e32 v136, 8, v137
	v_bfe_u32 v134, v137, 4, 2
	v_and_b32_e32 v137, 0xcf, v137
	v_lshlrev_b32_e32 v138, 2, v134
	v_lshl_or_b32 v140, s22, 8, v137
	v_add_u32_e32 v139, 12, v138
	v_ashrrev_i32_e32 v141, 31, v140
	v_cndmask_b32_e64 v138, v139, v138, s[4:5]
	v_lshlrev_b64 v[142:143], 11, v[140:141]
	s_lshl_b32 s44, s24, 8
	v_lshl_or_b32 v138, v136, 7, v138
	v_lshl_add_u64 v[142:143], s[8:9], 0, v[142:143]
	v_lshl_add_u64 v[142:143], s[44:45], 1, v[142:143]
	v_ashrrev_i32_e32 v139, 31, v138
	v_lshl_add_u64 v[142:143], v[138:139], 1, v[142:143]
	v_cvt_pk_bf16_f32 v137, v116, v117
	v_cvt_pk_bf16_f32 v144, v118, v119
	v_cvt_pk_bf16_f32 v145, v108, v109
	v_cvt_pk_bf16_f32 v146, v110, v111
	global_store_dwordx4 v[142:143], v[128:131], off
	s_nop 1
	v_mov_b32_e32 v128, v137
	v_mov_b32_e32 v130, v145
	v_mov_b32_e32 v129, v144
	v_mov_b32_e32 v131, v146
	v_permlane16_swap_b32_e32 v128, v130
	s_nop 0
	v_permlane16_swap_b32_e32 v129, v131
	s_and_saveexec_b64 s[4:5], vcc
	s_xor_b64 s[4:5], exec, s[4:5]
	v_mov_b32_e32 v131, v146
	v_mov_b32_e32 v130, v145
	s_andn2_saveexec_b64 s[4:5], s[4:5]
	v_mov_b32_e32 v128, v137
	v_mov_b32_e32 v129, v144
	s_or_b64 exec, exec, s[4:5]
	v_cvt_pk_bf16_f32 v137, v104, v105
	v_cvt_pk_bf16_f32 v144, v106, v107
	v_cvt_pk_bf16_f32 v145, v100, v101
	v_cvt_pk_bf16_f32 v146, v102, v103
	global_store_dwordx4 v[142:143], v[128:131], off offset:64
	s_nop 1
	v_mov_b32_e32 v128, v137
	v_mov_b32_e32 v130, v145
	v_mov_b32_e32 v129, v144
	v_mov_b32_e32 v131, v146
	v_permlane16_swap_b32_e32 v128, v130
	s_nop 0
	v_permlane16_swap_b32_e32 v129, v131
	s_and_saveexec_b64 s[4:5], vcc
	s_xor_b64 s[4:5], exec, s[4:5]
	v_mov_b32_e32 v131, v146
	v_mov_b32_e32 v130, v145
	s_andn2_saveexec_b64 s[4:5], s[4:5]
	v_mov_b32_e32 v128, v137
	v_mov_b32_e32 v129, v144
	s_or_b64 exec, exec, s[4:5]
	v_cvt_pk_bf16_f32 v137, v96, v97
	v_cvt_pk_bf16_f32 v144, v98, v99
	v_cvt_pk_bf16_f32 v145, v112, v113
	v_cvt_pk_bf16_f32 v146, v114, v115
	global_store_dwordx4 v[142:143], v[128:131], off offset:128
	s_nop 1
	v_mov_b32_e32 v128, v137
	v_mov_b32_e32 v130, v145
	v_mov_b32_e32 v129, v144
	v_mov_b32_e32 v131, v146
	v_permlane16_swap_b32_e32 v128, v130
	s_nop 0
	v_permlane16_swap_b32_e32 v129, v131
	s_and_saveexec_b64 s[4:5], vcc
	s_xor_b64 s[4:5], exec, s[4:5]
	v_mov_b32_e32 v131, v146
	v_mov_b32_e32 v130, v145
	s_andn2_saveexec_b64 s[4:5], s[4:5]
	v_mov_b32_e32 v128, v137
	v_mov_b32_e32 v129, v144
	s_or_b64 exec, exec, s[4:5]
	v_mul_f32_e32 v125, v125, v125
	v_mul_f32_e32 v117, v117, v117
	v_fmac_f32_e32 v125, v124, v124
	v_fmac_f32_e32 v117, v116, v116
	v_mul_f32_e32 v105, v105, v105
	v_fmac_f32_e32 v125, v126, v126
	v_fmac_f32_e32 v117, v118, v118
	v_fmac_f32_e32 v105, v104, v104
	v_mul_f32_e32 v97, v97, v97
	v_fmac_f32_e32 v125, v127, v127
	v_fmac_f32_e32 v117, v119, v119
	v_fmac_f32_e32 v105, v106, v106
	v_fmac_f32_e32 v97, v96, v96
	v_fmac_f32_e32 v125, v120, v120
	v_fmac_f32_e32 v117, v108, v108
	v_fmac_f32_e32 v105, v107, v107
	v_fmac_f32_e32 v97, v98, v98
	v_fmac_f32_e32 v125, v121, v121
	v_fmac_f32_e32 v117, v109, v109
	v_fmac_f32_e32 v105, v100, v100
	v_fmac_f32_e32 v97, v99, v99
	v_fmac_f32_e32 v125, v122, v122
	v_fmac_f32_e32 v117, v110, v110
	v_fmac_f32_e32 v105, v101, v101
	v_fmac_f32_e32 v97, v112, v112
	v_fmac_f32_e32 v125, v123, v123
	v_fmac_f32_e32 v117, v111, v111
	v_fmac_f32_e32 v105, v102, v102
	v_fmac_f32_e32 v97, v113, v113
	v_add_f32_e32 v108, v125, v117
	v_fmac_f32_e32 v105, v103, v103
	v_fmac_f32_e32 v97, v114, v114
	v_add_f32_e32 v100, v108, v105
	v_fmac_f32_e32 v97, v115, v115
	v_add_f32_e32 v96, v100, v97
	v_mov_b32_e32 v97, v96
	s_nop 1
	v_permlane16_swap_b32_e32 v96, v97
	v_add_f32_e32 v96, v96, v97
	v_mov_b32_e32 v97, v96
	v_cmp_eq_u32_e64 s[4:5], 0, v134
	v_ashrrev_i32_e32 v137, 31, v136
	v_permlane32_swap_b32_e32 v96, v97
	global_store_dwordx4 v[142:143], v[128:131], off offset:192
	s_and_saveexec_b64 s[12:13], s[4:5]
	s_cbranch_execz .LBB0_2374
	v_add_f32_e32 v98, v96, v97
	v_lshlrev_b64 v[96:97], 5, v[140:141]
	s_lshl_b32 s86, s24, 1
	s_mov_b32 s87, s45
	v_lshl_add_u64 v[96:97], s[10:11], 0, v[96:97]
	v_lshl_add_u64 v[96:97], s[86:87], 2, v[96:97]
	v_lshl_add_u64 v[96:97], v[136:137], 2, v[96:97]
	global_store_dword v[96:97], v98, off
